# RS-epilogue GEMMs: row scales preloaded at tile start into spare VGPRs; epilogue no longer drains the next tile's LDS-DMA prefetch (on top of peel)
# baseline (speedup 1.0000x reference)
; #define G lgrid()
;     __host__ __device__ bool next(int i, Unit& u) const {
;         const long L = (long)i * G + c; if (L >= nwg) return false;
;         int wgid = (int)L; { const int q = nwg / NXCD, r = nwg % NXCD, xcd = wgid % NXCD, off = wgid / NXCD; wgid = (xcd < r ? xcd * (q + 1) : r * (q + 1) + (xcd - r) * q) + off; }
;         const int nig = WGM * nN, gid = wgid / nig, fm = gid * WGM, gsz = (nM - fm) < WGM ? (nM - fm) : WGM;
;         u.pm = fm + ((wgid % nig) % gsz); u.pn = (wgid % nig) / gsz; return true;
;     __device__ __forceinline__ void operator()(const f32x4 (&acc)[2][2][4][2], const Unit& u, int wr, int wc, int fr, int fq) const {
;     ...
;         for (int ai = 0; ai < 2; ++ai)
; #pragma unroll
;             for (int m = 0; m < 4; ++m) rsv[ai][m] = RS ? rs_of(SS, row0 + ai * HALF + m * 16) : 1.0f;
.LBB0_13:
	v_lshl_add_u32 v250, s30, 8, v145
	v_ashrrev_i32_e32 v251, 31, v250
	v_lshl_add_u64 v[252:253], v[250:251], 2, s[8:9]
	global_load_dword v242, v[252:253], off
	global_load_dword v243, v[252:253], off offset:64
	global_load_dword v244, v[252:253], off offset:128
	global_load_dword v245, v[252:253], off offset:192
	global_load_dword v246, v[252:253], off offset:512
	global_load_dword v247, v[252:253], off offset:576
	global_load_dword v248, v[252:253], off offset:640
	global_load_dword v249, v[252:253], off offset:704
	s_add_i32 s52, s52, 1
	s_mul_i32 s4, s52, s57
	s_mul_hi_u32 s5, s52, s2
	s_add_i32 s5, s5, s4
	s_mul_i32 s4, s52, s2
	s_add_u32 s26, s4, s33
	s_addc_u32 s27, s5, s45
	v_cmp_gt_i64_e32 vcc, s[26:27], v[142:143]
	v_cmp_lt_i64_e64 s[4:5], s[26:27], v[140:141]
	s_cbranch_vccnz .LBB0_15
	s_ashr_i32 s22, s26, 31
	s_lshr_b32 s22, s22, 29
	s_add_i32 s22, s26, s22
	s_ashr_i32 s23, s22, 3
	s_and_b32 s22, s22, -8
	s_sub_i32 s22, s26, s22
	s_cmp_lt_i32 s22, 0
	s_cselect_b32 s24, s46, 0x240
	s_mul_i32 s22, s22, s24
	s_add_i32 s22, s22, s23
	s_mul_hi_i32 s23, s22, 0x2aaaaaab
	s_lshr_b32 s24, s23, 31
	s_ashr_i32 s23, s23, 4
	s_add_i32 s23, s23, s24
	s_lshl_b32 s24, s23, 2
	s_sub_i32 s25, 0xc0, s24
	s_min_i32 s25, s25, 4
	s_abs_i32 s26, s25
	v_cvt_f32_u32_e32 v0, s26
	s_sub_i32 s28, 0, s26
	s_mulk_i32 s23, 0x60
	s_sub_i32 s23, s22, s23
	v_rcp_iflag_f32_e32 v0, v0
	s_abs_i32 s22, s23
	s_xor_b32 s27, s23, s25
	s_ashr_i32 s27, s27, 31
	v_mul_f32_e32 v0, 0x4f7ffffe, v0
	v_cvt_u32_f32_e32 v0, v0
	s_nop 0
	v_readfirstlane_b32 s29, v0
	s_mul_i32 s28, s28, s29
	s_mul_hi_u32 s28, s29, s28
	s_add_i32 s29, s29, s28
	s_mul_hi_u32 s28, s22, s29
	s_mul_i32 s29, s28, s26
	s_sub_i32 s22, s22, s29
	s_add_i32 s38, s28, 1
	s_sub_i32 s29, s22, s26
	s_cmp_ge_u32 s22, s26
	s_cselect_b32 s28, s38, s28
	s_cselect_b32 s22, s29, s22
	s_add_i32 s29, s28, 1
	s_cmp_ge_u32 s22, s26
	s_cselect_b32 s22, s29, s28
	s_xor_b32 s22, s22, s27
	s_sub_i32 s22, s22, s27
	s_mul_i32 s25, s22, s25
	s_sub_i32 s23, s23, s25
	s_add_i32 s24, s24, s23

; __device__ __forceinline__ unsigned cvt_pk_bf16(float lo, float hi) { f32x2c_t v = {lo, hi}; bf16x2c_t b = __builtin_convertvector(v, bf16x2c_t); return __builtin_bit_cast(unsigned, b); }
;     __device__ __forceinline__ void operator()(const f32x4 (&acc)[2][2][4][2], const Unit& u, int wr, int wc, int fr, int fq) const {
;         const int row0 = u.pm * BM + wr * 64 + fr; int colt = u.pn * BM; bf16_t* base = O;
;         { const int t = colt / split_cols; base += (size_t)t * split_stride; colt -= t * split_cols; }
;         const int col0 = colt + wc * 32 + 8 * fq;
;         float rsv[2][4];
; #pragma unroll
;         for (int ai = 0; ai < 2; ++ai)
; #pragma unroll
;             for (int m = 0; m < 4; ++m) rsv[ai][m] = RS ? rs_of(SS, row0 + ai * HALF + m * 16) : 1.0f;
; #pragma unroll
;         for (int ai = 0; ai < 2; ++ai)
; #pragma unroll
;             for (int m = 0; m < 4; ++m) { bf16_t* rowp = base + (size_t)(row0 + ai * HALF + m * 16) * ldc + col0;
;                 const float rs = rsv[ai][m];
; #pragma unroll
;                 for (int bj = 0; bj < 2; ++bj) { f32x4 v0 = acc[ai][bj][m][0], v1 = acc[ai][bj][m][1];
;                     if (RS) { v0 = v0 * rs; v1 = v1 * rs; }
;                     u32x4 w; w.x = cvt_pk_bf16(v0[0], v0[1]); w.y = cvt_pk_bf16(v0[2], v0[3]); w.z = cvt_pk_bf16(v1[0], v1[1]); w.w = cvt_pk_bf16(v1[2], v1[3]);
;                     *(u32x4*)(rowp + bj * HALF) = w; } }
.LBB0_19:
	v_lshl_add_u32 v146, s30, 8, v145
	v_ashrrev_i32_e32 v147, 31, v146
	v_or_b32_e32 v158, 16, v146
	v_or_b32_e32 v162, 32, v146
	v_lshl_add_u64 v[154:155], v[146:147], 2, s[8:9]
	v_ashrrev_i32_e32 v159, 31, v158
	v_ashrrev_i32_e32 v163, 31, v162
	v_mov_b32_e32 v156, v242
	v_lshl_add_u64 v[160:161], v[158:159], 2, s[8:9]
	v_lshl_add_u64 v[164:165], v[162:163], 2, s[8:9]
	v_mov_b32_e32 v160, v243
	v_or_b32_e32 v166, 48, v146
	v_mov_b32_e32 v164, v244
	v_ashrrev_i32_e32 v167, 31, v166
	v_lshl_add_u64 v[168:169], v[166:167], 2, s[8:9]
	v_mov_b32_e32 v168, v245
	s_nop 0
	v_mov_b32_e32 v170, v246
	v_mov_b32_e32 v172, v247
	v_mov_b32_e32 v174, v248
	v_mov_b32_e32 v144, v249
	s_ashr_i32 s23, s64, 31
	s_lshr_b32 s23, s23, 30
	s_add_i32 s23, s64, s23
	s_ashr_i32 s23, s23, 2
	s_mul_i32 s30, s23, 0x6000000
	s_mul_hi_i32 s25, s23, 0x6000000
	s_add_u32 s34, s53, s30
	v_lshl_or_b32 v153, s64, 8, v149
	s_addc_u32 s35, s54, s25
	s_lshl_b32 s23, s23, 10
	v_subrev_u32_e32 v154, s23, v153
	v_ashrrev_i32_e32 v155, 31, v154
	v_lshlrev_b64 v[146:147], 11, v[146:147]
	v_lshlrev_b64 v[158:159], 11, v[158:159]
	v_lshlrev_b64 v[162:163], 11, v[162:163]
	v_lshl_add_u64 v[154:155], v[154:155], 1, s[34:35]
	v_lshl_add_u64 v[146:147], v[154:155], 0, v[146:147]
	v_lshl_add_u64 v[158:159], v[154:155], 0, v[158:159]
	v_lshl_add_u64 v[162:163], v[154:155], 0, v[162:163]
	s_waitcnt vmcnt(8)
	v_pk_mul_f32 v[126:127], v[126:127], v[156:157] op_sel_hi:[1,0]
	v_pk_mul_f32 v[124:125], v[124:125], v[156:157] op_sel_hi:[1,0]
	v_pk_mul_f32 v[122:123], v[122:123], v[156:157] op_sel_hi:[1,0]
	v_pk_mul_f32 v[120:121], v[120:121], v[156:157] op_sel_hi:[1,0]
	v_pk_mul_f32 v[110:111], v[110:111], v[156:157] op_sel_hi:[1,0]
	v_pk_mul_f32 v[108:109], v[108:109], v[156:157] op_sel_hi:[1,0]
	v_pk_mul_f32 v[176:177], v[106:107], v[156:157] op_sel_hi:[1,0]
	v_pk_mul_f32 v[156:157], v[104:105], v[156:157] op_sel_hi:[1,0]
	v_cvt_pk_bf16_f32 v104, v124, v125
	v_cvt_pk_bf16_f32 v105, v126, v127
	v_cvt_pk_bf16_f32 v107, v122, v123
	v_pk_mul_f32 v[118:119], v[118:119], v[160:161] op_sel_hi:[1,0]
	v_pk_mul_f32 v[116:117], v[116:117], v[160:161] op_sel_hi:[1,0]
	v_pk_mul_f32 v[114:115], v[114:115], v[160:161] op_sel_hi:[1,0]
	v_pk_mul_f32 v[112:113], v[112:113], v[160:161] op_sel_hi:[1,0]
	v_pk_mul_f32 v[122:123], v[86:87], v[164:165] op_sel_hi:[1,0]
	v_pk_mul_f32 v[124:125], v[84:85], v[164:165] op_sel_hi:[1,0]
	v_pk_mul_f32 v[126:127], v[74:75], v[164:165] op_sel_hi:[1,0]
	v_pk_mul_f32 v[74:75], v[72:73], v[164:165] op_sel_hi:[1,0]
	v_cvt_pk_bf16_f32 v106, v120, v121
	v_pk_mul_f32 v[94:95], v[94:95], v[160:161] op_sel_hi:[1,0]
	v_pk_mul_f32 v[92:93], v[92:93], v[160:161] op_sel_hi:[1,0]
	v_pk_mul_f32 v[120:121], v[90:91], v[160:161] op_sel_hi:[1,0]
	v_pk_mul_f32 v[90:91], v[88:89], v[160:161] op_sel_hi:[1,0]
	v_pk_mul_f32 v[102:103], v[102:103], v[164:165] op_sel_hi:[1,0]
	v_pk_mul_f32 v[100:101], v[100:101], v[164:165] op_sel_hi:[1,0]
	v_pk_mul_f32 v[98:99], v[98:99], v[164:165] op_sel_hi:[1,0]
	v_pk_mul_f32 v[96:97], v[96:97], v[164:165] op_sel_hi:[1,0]
	v_cvt_pk_bf16_f32 v84, v116, v117
	v_cvt_pk_bf16_f32 v85, v118, v119
	v_cvt_pk_bf16_f32 v86, v112, v113
	v_cvt_pk_bf16_f32 v87, v114, v115
	v_cvt_pk_bf16_f32 v72, v124, v125
	v_cvt_pk_bf16_f32 v73, v122, v123
	v_cvt_pk_bf16_f32 v74, v74, v75
	v_cvt_pk_bf16_f32 v75, v126, v127
	v_cvt_pk_bf16_f32 v108, v108, v109
	v_cvt_pk_bf16_f32 v109, v110, v111
	v_cvt_pk_bf16_f32 v110, v156, v157
	v_cvt_pk_bf16_f32 v111, v176, v177
	global_store_dwordx4 v[146:147], v[104:107], off
	global_store_dwordx4 v[146:147], v[108:111], off offset:256
	v_cvt_pk_bf16_f32 v88, v92, v93
	v_cvt_pk_bf16_f32 v89, v94, v95
	v_cvt_pk_bf16_f32 v90, v90, v91
	v_cvt_pk_bf16_f32 v91, v120, v121
	v_cvt_pk_bf16_f32 v92, v100, v101
	v_cvt_pk_bf16_f32 v93, v102, v103
	v_cvt_pk_bf16_f32 v94, v96, v97
	v_cvt_pk_bf16_f32 v95, v98, v99
	global_store_dwordx4 v[158:159], v[84:87], off
	global_store_dwordx4 v[158:159], v[88:91], off offset:256
	global_store_dwordx4 v[162:163], v[92:95], off
	global_store_dwordx4 v[162:163], v[72:75], off offset:256
	v_pk_mul_f32 v[78:79], v[78:79], v[168:169] op_sel_hi:[1,0]
	v_pk_mul_f32 v[76:77], v[76:77], v[168:169] op_sel_hi:[1,0]
	v_lshlrev_b64 v[72:73], 11, v[166:167]
	v_lshl_add_u64 v[84:85], v[154:155], 0, v[72:73]
	v_pk_mul_f32 v[74:75], v[82:83], v[168:169] op_sel_hi:[1,0]
	v_pk_mul_f32 v[72:73], v[80:81], v[168:169] op_sel_hi:[1,0]
	v_pk_mul_f32 v[70:71], v[70:71], v[168:169] op_sel_hi:[1,0]
	v_cvt_pk_bf16_f32 v72, v72, v73
	v_cvt_pk_bf16_f32 v73, v74, v75
	v_cvt_pk_bf16_f32 v74, v76, v77
; __device__ __forceinline__ unsigned cvt_pk_bf16(float lo, float hi) { f32x2c_t v = {lo, hi}; bf16x2c_t b = __builtin_convertvector(v, bf16x2c_t); return __builtin_bit_cast(unsigned, b); }
; #define PG8_BAR __builtin_amdgcn_s_barrier()
;     __device__ __forceinline__ void operator()(const f32x4 (&acc)[2][2][4][2], const Unit& u, int wr, int wc, int fr, int fq) const {
;     ...
;             for (int m = 0; m < 4; ++m) { bf16_t* rowp = base + (size_t)(row0 + ai * HALF + m * 16) * ldc + col0;
;                 const float rs = rsv[ai][m];
; #pragma unroll
;                 for (int bj = 0; bj < 2; ++bj) { f32x4 v0 = acc[ai][bj][m][0], v1 = acc[ai][bj][m][1];
;                     if (RS) { v0 = v0 * rs; v1 = v1 * rs; }
;                     u32x4 w; w.x = cvt_pk_bf16(v0[0], v0[1]); w.y = cvt_pk_bf16(v0[2], v0[3]); w.z = cvt_pk_bf16(v1[0], v1[1]); w.w = cvt_pk_bf16(v1[2], v1[3]);
;                     *(u32x4*)(rowp + bj * HALF) = w; } }
; template <class Epi, class Sched, bool ALIGN_EPI = false, bool SP2 = false>
; __device__ __forceinline__ void gemm_phase(PG8_LAS unsigned char* lds, const Gemm g, const Sched& S, const Epi& E) {
;     ...
;         if constexpr (ALIGN_EPI) { if (wr == 0) PG8_BAR; }
;         if constexpr (!Epi::AFTER_DRAIN) { E(acc, cur, wr, wc, fr, fq); S.done(cur); }
;         if (!has_next) break;
; #pragma unroll
;         for (int a = 0; a < 2; ++a)
; #pragma unroll
;             for (int b = 0; b < 2; ++b)
; #pragma unroll
;                 for (int m = 0; m < 4; ++m)
; #pragma unroll
;                     for (int n = 0; n < 2; ++n) acc[a][b][m][n] = (f32x4){0.f, 0.f, 0.f, 0.f};
;         cur = nxt; cA = nA; cB = nB; ++ui;
;         if constexpr (ALIGN_EPI) { if (wr == 1) PG8_BAR; }
	v_cvt_pk_bf16_f32 v75, v78, v79
	global_store_dwordx4 v[84:85], v[72:75], off
	v_pk_mul_f32 v[68:69], v[68:69], v[168:169] op_sel_hi:[1,0]
	v_pk_mul_f32 v[60:61], v[60:61], v[170:171] op_sel_hi:[1,0]
	v_pk_mul_f32 v[72:73], v[66:67], v[168:169] op_sel_hi:[1,0]
	v_pk_mul_f32 v[66:67], v[64:65], v[168:169] op_sel_hi:[1,0]
	v_cvt_pk_bf16_f32 v64, v68, v69
	v_cvt_pk_bf16_f32 v65, v70, v71
	v_cvt_pk_bf16_f32 v66, v66, v67
	v_cvt_pk_bf16_f32 v67, v72, v73
	global_store_dwordx4 v[84:85], v[64:67], off offset:256
	v_pk_mul_f32 v[62:63], v[62:63], v[170:171] op_sel_hi:[1,0]
	v_pk_mul_f32 v[50:51], v[50:51], v[170:171] op_sel_hi:[1,0]
	v_pk_mul_f32 v[66:67], v[58:59], v[170:171] op_sel_hi:[1,0]
	v_pk_mul_f32 v[58:59], v[56:57], v[170:171] op_sel_hi:[1,0]
	v_cvt_pk_bf16_f32 v56, v60, v61
	v_add_co_u32_e32 v60, vcc, s60, v146
	v_cvt_pk_bf16_f32 v57, v62, v63
	v_cvt_pk_bf16_f32 v58, v58, v59
	v_cvt_pk_bf16_f32 v59, v66, v67
	v_addc_co_u32_e32 v61, vcc, 0, v147, vcc
	global_store_dwordx4 v[60:61], v[56:59], off
	v_pk_mul_f32 v[48:49], v[48:49], v[170:171] op_sel_hi:[1,0]
	v_lshl_add_u64 v[64:65], v[146:147], 0, s[14:15]
	v_pk_mul_f32 v[56:57], v[42:43], v[170:171] op_sel_hi:[1,0]
	v_pk_mul_f32 v[42:43], v[40:41], v[170:171] op_sel_hi:[1,0]
	v_cvt_pk_bf16_f32 v40, v48, v49
	v_cvt_pk_bf16_f32 v41, v50, v51
	v_cvt_pk_bf16_f32 v42, v42, v43
	v_cvt_pk_bf16_f32 v43, v56, v57
	global_store_dwordx4 v[64:65], v[40:43], off offset:256
	v_pk_mul_f32 v[44:45], v[44:45], v[172:173] op_sel_hi:[1,0]
	v_pk_mul_f32 v[46:47], v[46:47], v[172:173] op_sel_hi:[1,0]
	v_pk_mul_f32 v[42:43], v[54:55], v[172:173] op_sel_hi:[1,0]
	v_pk_mul_f32 v[40:41], v[52:53], v[172:173] op_sel_hi:[1,0]
	v_pk_mul_f32 v[34:35], v[34:35], v[172:173] op_sel_hi:[1,0]
	v_cvt_pk_bf16_f32 v40, v40, v41
	v_cvt_pk_bf16_f32 v41, v42, v43
	v_cvt_pk_bf16_f32 v42, v44, v45
	v_add_co_u32_e32 v44, vcc, s61, v146
	v_cvt_pk_bf16_f32 v43, v46, v47
	s_nop 0
	v_addc_co_u32_e32 v45, vcc, 0, v147, vcc
	global_store_dwordx4 v[44:45], v[40:43], off
	v_pk_mul_f32 v[32:33], v[32:33], v[172:173] op_sel_hi:[1,0]
	v_lshl_add_u64 v[48:49], v[146:147], 0, s[16:17]
	v_pk_mul_f32 v[40:41], v[26:27], v[172:173] op_sel_hi:[1,0]
	v_pk_mul_f32 v[26:27], v[24:25], v[172:173] op_sel_hi:[1,0]
	v_cvt_pk_bf16_f32 v24, v32, v33
	v_cvt_pk_bf16_f32 v25, v34, v35
	v_cvt_pk_bf16_f32 v26, v26, v27
	v_cvt_pk_bf16_f32 v27, v40, v41
	global_store_dwordx4 v[48:49], v[24:27], off offset:256
	v_pk_mul_f32 v[28:29], v[28:29], v[174:175] op_sel_hi:[1,0]
	v_pk_mul_f32 v[30:31], v[30:31], v[174:175] op_sel_hi:[1,0]
	v_pk_mul_f32 v[26:27], v[38:39], v[174:175] op_sel_hi:[1,0]
	v_pk_mul_f32 v[24:25], v[36:37], v[174:175] op_sel_hi:[1,0]
	v_pk_mul_f32 v[18:19], v[18:19], v[174:175] op_sel_hi:[1,0]
	v_cvt_pk_bf16_f32 v24, v24, v25
	v_cvt_pk_bf16_f32 v25, v26, v27
	v_cvt_pk_bf16_f32 v26, v28, v29
	v_add_co_u32_e32 v28, vcc, s62, v146
	v_cvt_pk_bf16_f32 v27, v30, v31
	s_nop 0
	v_addc_co_u32_e32 v29, vcc, 0, v147, vcc
	global_store_dwordx4 v[28:29], v[24:27], off
	v_pk_mul_f32 v[16:17], v[16:17], v[174:175] op_sel_hi:[1,0]
	v_lshl_add_u64 v[32:33], v[146:147], 0, s[18:19]
	v_pk_mul_f32 v[24:25], v[10:11], v[174:175] op_sel_hi:[1,0]
	v_pk_mul_f32 v[10:11], v[8:9], v[174:175] op_sel_hi:[1,0]
	v_cvt_pk_bf16_f32 v8, v16, v17
	v_cvt_pk_bf16_f32 v9, v18, v19
	v_cvt_pk_bf16_f32 v10, v10, v11
	v_cvt_pk_bf16_f32 v11, v24, v25
	global_store_dwordx4 v[32:33], v[8:11], off offset:256
	v_pk_mul_f32 v[12:13], v[12:13], v[144:145] op_sel_hi:[1,0]
	v_pk_mul_f32 v[14:15], v[14:15], v[144:145] op_sel_hi:[1,0]
	v_pk_mul_f32 v[10:11], v[22:23], v[144:145] op_sel_hi:[1,0]
	v_pk_mul_f32 v[8:9], v[20:21], v[144:145] op_sel_hi:[1,0]
	v_pk_mul_f32 v[6:7], v[6:7], v[144:145] op_sel_hi:[1,0]
	v_cvt_pk_bf16_f32 v8, v8, v9
	v_cvt_pk_bf16_f32 v9, v10, v11
	v_cvt_pk_bf16_f32 v10, v12, v13
	v_add_co_u32_e32 v12, vcc, s63, v146
	v_cvt_pk_bf16_f32 v11, v14, v15
	s_nop 0
	v_addc_co_u32_e32 v13, vcc, 0, v147, vcc
	global_store_dwordx4 v[12:13], v[8:11], off
	v_pk_mul_f32 v[4:5], v[4:5], v[144:145] op_sel_hi:[1,0]
	v_lshl_add_u64 v[16:17], v[146:147], 0, s[20:21]
	v_pk_mul_f32 v[8:9], v[2:3], v[144:145] op_sel_hi:[1,0]
	v_pk_mul_f32 v[2:3], v[0:1], v[144:145] op_sel_hi:[1,0]
	v_cvt_pk_bf16_f32 v0, v4, v5
	v_cvt_pk_bf16_f32 v1, v6, v7
	v_cvt_pk_bf16_f32 v2, v2, v3
	v_cvt_pk_bf16_f32 v3, v8, v9
	s_andn2_b64 vcc, exec, s[4:5]
	s_mov_b64 s[4:5], -1
	global_store_dwordx4 v[16:17], v[0:3], off offset:256
	s_cbranch_vccnz .LBB0_12
	s_andn2_b64 vcc, exec, s[6:7]
	s_cbranch_vccnz .LBB0_11
	s_barrier
	s_branch .LBB0_11

; #define G lgrid()
;     __host__ __device__ bool next(int i, Unit& u) const {
;         const long L = (long)i * G + c; if (L >= nwg) return false;
;         int wgid = (int)L; { const int q = nwg / NXCD, r = nwg % NXCD, xcd = wgid % NXCD, off = wgid / NXCD; wgid = (xcd < r ? xcd * (q + 1) : r * (q + 1) + (xcd - r) * q) + off; }
;         const int nig = WGM * nN, gid = wgid / nig, fm = gid * WGM, gsz = (nM - fm) < WGM ? (nM - fm) : WGM;
;         u.pm = fm + ((wgid % nig) % gsz); u.pn = (wgid % nig) / gsz; return true;
;     __device__ __forceinline__ void operator()(const f32x4 (&acc)[2][2][4][2], const Unit& u, int wr, int wc, int fr, int fq) const {
;     ...
;         for (int ai = 0; ai < 2; ++ai)
; #pragma unroll
;             for (int m = 0; m < 4; ++m) rsv[ai][m] = RS ? rs_of(SS, row0 + ai * HALF + m * 16) : 1.0f;
.LBB0_518:
	v_lshl_add_u32 v250, s24, 8, v153
	v_ashrrev_i32_e32 v251, 31, v250
	v_lshl_add_u64 v[252:253], v[250:251], 2, s[12:13]
	global_load_dword v242, v[252:253], off
	global_load_dword v243, v[252:253], off offset:64
	global_load_dword v244, v[252:253], off offset:128
	global_load_dword v245, v[252:253], off offset:192
	global_load_dword v246, v[252:253], off offset:512
	global_load_dword v247, v[252:253], off offset:576
	global_load_dword v248, v[252:253], off offset:640
	global_load_dword v249, v[252:253], off offset:704
	s_add_i32 s57, s57, 1
	s_mul_i32 s17, s57, s34
	s_mul_hi_u32 s19, s57, s5
	s_add_i32 s19, s19, s17
	s_mul_i32 s17, s57, s5
	s_add_u32 s20, s17, s8
	s_addc_u32 s21, s19, s9
	v_mov_b64_e32 v[0:1], 0x1200
	v_cmp_gt_i64_e32 vcc, s[20:21], v[138:139]
	v_cmp_lt_i64_e64 s[40:41], s[20:21], v[0:1]
	s_cbranch_vccnz .LBB0_520
	s_ashr_i32 s16, s20, 31
	s_lshr_b32 s16, s16, 29
	s_add_i32 s16, s20, s16
	s_ashr_i32 s17, s16, 3
	s_and_b32 s16, s16, -8
	s_sub_i32 s16, s20, s16
	s_cmp_lt_i32 s16, 0
	s_cselect_b32 s18, s76, 0x240
	s_mul_i32 s16, s16, s18
	s_add_i32 s16, s16, s17
	s_mul_hi_i32 s17, s16, 0x2aaaaaab
	s_lshr_b32 s18, s17, 31
	s_ashr_i32 s17, s17, 4
	s_add_i32 s17, s17, s18
	s_lshl_b32 s18, s17, 2
	s_sub_i32 s19, 0xc0, s18
	s_min_i32 s19, s19, 4
	s_abs_i32 s20, s19
	v_cvt_f32_u32_e32 v0, s20
	s_sub_i32 s22, 0, s20
	s_mulk_i32 s17, 0x60
	s_sub_i32 s17, s16, s17
	v_rcp_iflag_f32_e32 v0, v0
	s_abs_i32 s16, s17
	s_xor_b32 s21, s17, s19
	s_ashr_i32 s21, s21, 31
	v_mul_f32_e32 v0, 0x4f7ffffe, v0
	v_cvt_u32_f32_e32 v0, v0
	s_nop 0
	v_readfirstlane_b32 s23, v0
	s_mul_i32 s22, s22, s23
	s_mul_hi_u32 s22, s23, s22
	s_add_i32 s23, s23, s22
	s_mul_hi_u32 s22, s16, s23
	s_mul_i32 s23, s22, s20
	s_sub_i32 s16, s16, s23
	s_add_i32 s30, s22, 1
	s_sub_i32 s23, s16, s20
	s_cmp_ge_u32 s16, s20
	s_cselect_b32 s22, s30, s22
	s_cselect_b32 s16, s23, s16
	s_add_i32 s23, s22, 1
	s_cmp_ge_u32 s16, s20
	s_cselect_b32 s16, s23, s22
	s_xor_b32 s16, s16, s21
	s_sub_i32 s16, s16, s21
	s_mul_i32 s19, s16, s19
	s_sub_i32 s17, s17, s19
	s_add_i32 s18, s18, s17

; __device__ __forceinline__ unsigned cvt_pk_bf16(float lo, float hi) { f32x2c_t v = {lo, hi}; bf16x2c_t b = __builtin_convertvector(v, bf16x2c_t); return __builtin_bit_cast(unsigned, b); }
;     __device__ __forceinline__ void operator()(const f32x4 (&acc)[2][2][4][2], const Unit& u, int wr, int wc, int fr, int fq) const {
;         const int row0 = u.pm * BM + wr * 64 + fr; int colt = u.pn * BM; bf16_t* base = O;
;         { const int t = colt / split_cols; base += (size_t)t * split_stride; colt -= t * split_cols; }
;         const int col0 = colt + wc * 32 + 8 * fq;
;         float rsv[2][4];
; #pragma unroll
;         for (int ai = 0; ai < 2; ++ai)
; #pragma unroll
;             for (int m = 0; m < 4; ++m) rsv[ai][m] = RS ? rs_of(SS, row0 + ai * HALF + m * 16) : 1.0f;
; #pragma unroll
;         for (int ai = 0; ai < 2; ++ai)
; #pragma unroll
;             for (int m = 0; m < 4; ++m) { bf16_t* rowp = base + (size_t)(row0 + ai * HALF + m * 16) * ldc + col0;
;                 const float rs = rsv[ai][m];
; #pragma unroll
;                 for (int bj = 0; bj < 2; ++bj) { f32x4 v0 = acc[ai][bj][m][0], v1 = acc[ai][bj][m][1];
;                     if (RS) { v0 = v0 * rs; v1 = v1 * rs; }
;                     u32x4 w; w.x = cvt_pk_bf16(v0[0], v0[1]); w.y = cvt_pk_bf16(v0[2], v0[3]); w.z = cvt_pk_bf16(v1[0], v1[1]); w.w = cvt_pk_bf16(v1[2], v1[3]);
;                     *(u32x4*)(rowp + bj * HALF) = w; } }
.LBB0_524:
	v_lshl_add_u32 v130, s24, 8, v153
	v_ashrrev_i32_e32 v131, 31, v130
	v_or_b32_e32 v154, 16, v130
	v_or_b32_e32 v164, 32, v130
	v_lshl_add_u64 v[132:133], v[130:131], 2, s[12:13]
	v_ashrrev_i32_e32 v155, 31, v154
	v_ashrrev_i32_e32 v165, 31, v164
	v_mov_b32_e32 v160, v242
	v_lshl_add_u64 v[162:163], v[154:155], 2, s[12:13]
	v_lshl_add_u64 v[166:167], v[164:165], 2, s[12:13]
	v_mov_b32_e32 v162, v243
	v_or_b32_e32 v168, 48, v130
	v_mov_b32_e32 v166, v244
	v_ashrrev_i32_e32 v169, 31, v168
	v_lshl_add_u64 v[170:171], v[168:169], 2, s[12:13]
	v_mov_b32_e32 v170, v245
	s_nop 0
	v_mov_b32_e32 v174, v246
	v_mov_b32_e32 v176, v247
	v_mov_b32_e32 v178, v248
	v_mov_b32_e32 v152, v249
	s_ashr_i32 s17, s25, 31
	s_lshr_b32 s17, s17, 29
	s_add_i32 s17, s25, s17
	s_ashr_i32 s17, s17, 3
	s_mul_i32 s24, s17, 0xc000000
	s_mul_hi_i32 s19, s17, 0xc000000
	s_add_u32 s24, s48, s24
	v_lshl_or_b32 v134, s25, 8, v157
	s_addc_u32 s25, s54, s19
	s_lshl_b32 s17, s17, 11
	v_subrev_u32_e32 v132, s17, v134
	v_ashrrev_i32_e32 v133, 31, v132
	v_lshlrev_b64 v[130:131], 12, v[130:131]
	v_lshlrev_b64 v[172:173], 12, v[154:155]
	v_lshl_add_u64 v[132:133], v[132:133], 1, s[24:25]
	v_lshlrev_b64 v[164:165], 12, v[164:165]
	v_lshl_add_u64 v[154:155], v[132:133], 0, v[130:131]
	v_lshl_add_u64 v[130:131], v[132:133], 0, v[172:173]
	v_lshl_add_u64 v[164:165], v[132:133], 0, v[164:165]
	s_mov_b32 s17, 0x80000
	s_mov_b64 s[24:25], 0x80000
	s_waitcnt vmcnt(8)
	v_pk_mul_f32 v[126:127], v[126:127], v[160:161] op_sel_hi:[1,0]
	v_pk_mul_f32 v[124:125], v[124:125], v[160:161] op_sel_hi:[1,0]
	v_pk_mul_f32 v[122:123], v[122:123], v[160:161] op_sel_hi:[1,0]
	v_pk_mul_f32 v[120:121], v[120:121], v[160:161] op_sel_hi:[1,0]
	v_pk_mul_f32 v[110:111], v[110:111], v[160:161] op_sel_hi:[1,0]
	v_pk_mul_f32 v[108:109], v[108:109], v[160:161] op_sel_hi:[1,0]
	v_pk_mul_f32 v[172:173], v[106:107], v[160:161] op_sel_hi:[1,0]
	v_pk_mul_f32 v[160:161], v[104:105], v[160:161] op_sel_hi:[1,0]
	v_cvt_pk_bf16_f32 v104, v124, v125
	v_cvt_pk_bf16_f32 v105, v126, v127
	v_cvt_pk_bf16_f32 v107, v122, v123
	v_pk_mul_f32 v[118:119], v[118:119], v[162:163] op_sel_hi:[1,0]
	v_pk_mul_f32 v[116:117], v[116:117], v[162:163] op_sel_hi:[1,0]
	v_pk_mul_f32 v[114:115], v[114:115], v[162:163] op_sel_hi:[1,0]
	v_pk_mul_f32 v[112:113], v[112:113], v[162:163] op_sel_hi:[1,0]
	v_pk_mul_f32 v[122:123], v[86:87], v[166:167] op_sel_hi:[1,0]
	v_pk_mul_f32 v[124:125], v[84:85], v[166:167] op_sel_hi:[1,0]
	v_pk_mul_f32 v[126:127], v[74:75], v[166:167] op_sel_hi:[1,0]
	v_pk_mul_f32 v[74:75], v[72:73], v[166:167] op_sel_hi:[1,0]
	v_cvt_pk_bf16_f32 v106, v120, v121
	v_pk_mul_f32 v[94:95], v[94:95], v[162:163] op_sel_hi:[1,0]
	v_pk_mul_f32 v[92:93], v[92:93], v[162:163] op_sel_hi:[1,0]
	v_pk_mul_f32 v[120:121], v[90:91], v[162:163] op_sel_hi:[1,0]
	v_pk_mul_f32 v[90:91], v[88:89], v[162:163] op_sel_hi:[1,0]
	v_pk_mul_f32 v[102:103], v[102:103], v[166:167] op_sel_hi:[1,0]
	v_pk_mul_f32 v[100:101], v[100:101], v[166:167] op_sel_hi:[1,0]
	v_pk_mul_f32 v[98:99], v[98:99], v[166:167] op_sel_hi:[1,0]
	v_pk_mul_f32 v[96:97], v[96:97], v[166:167] op_sel_hi:[1,0]
	v_cvt_pk_bf16_f32 v84, v116, v117
	v_cvt_pk_bf16_f32 v85, v118, v119
	v_cvt_pk_bf16_f32 v86, v112, v113
	v_cvt_pk_bf16_f32 v87, v114, v115
	v_cvt_pk_bf16_f32 v72, v124, v125
	v_cvt_pk_bf16_f32 v73, v122, v123
	v_cvt_pk_bf16_f32 v74, v74, v75
	v_cvt_pk_bf16_f32 v75, v126, v127
	v_cvt_pk_bf16_f32 v108, v108, v109
	v_cvt_pk_bf16_f32 v109, v110, v111
	v_cvt_pk_bf16_f32 v110, v160, v161
	v_cvt_pk_bf16_f32 v111, v172, v173
	global_store_dwordx4 v[154:155], v[104:107], off
	global_store_dwordx4 v[154:155], v[108:111], off offset:256
	v_cvt_pk_bf16_f32 v88, v92, v93
	v_cvt_pk_bf16_f32 v89, v94, v95
	v_cvt_pk_bf16_f32 v90, v90, v91
	v_cvt_pk_bf16_f32 v91, v120, v121
	v_cvt_pk_bf16_f32 v92, v100, v101
	v_cvt_pk_bf16_f32 v93, v102, v103
	v_cvt_pk_bf16_f32 v94, v96, v97
	v_cvt_pk_bf16_f32 v95, v98, v99
	global_store_dwordx4 v[130:131], v[84:87], off
	global_store_dwordx4 v[130:131], v[88:91], off offset:256
	global_store_dwordx4 v[164:165], v[92:95], off
	global_store_dwordx4 v[164:165], v[72:75], off offset:256
	v_pk_mul_f32 v[78:79], v[78:79], v[170:171] op_sel_hi:[1,0]
	v_pk_mul_f32 v[76:77], v[76:77], v[170:171] op_sel_hi:[1,0]
	v_lshlrev_b64 v[72:73], 12, v[168:169]
	v_lshl_add_u64 v[84:85], v[132:133], 0, v[72:73]
	v_pk_mul_f32 v[74:75], v[82:83], v[170:171] op_sel_hi:[1,0]
	v_pk_mul_f32 v[72:73], v[80:81], v[170:171] op_sel_hi:[1,0]
	v_pk_mul_f32 v[70:71], v[70:71], v[170:171] op_sel_hi:[1,0]
	v_cvt_pk_bf16_f32 v72, v72, v73
	v_cvt_pk_bf16_f32 v73, v74, v75
	v_cvt_pk_bf16_f32 v74, v76, v77
; __device__ __forceinline__ unsigned cvt_pk_bf16(float lo, float hi) { f32x2c_t v = {lo, hi}; bf16x2c_t b = __builtin_convertvector(v, bf16x2c_t); return __builtin_bit_cast(unsigned, b); }
; #define PG8_BAR __builtin_amdgcn_s_barrier()
;     __device__ __forceinline__ void operator()(const f32x4 (&acc)[2][2][4][2], const Unit& u, int wr, int wc, int fr, int fq) const {
;     ...
;             for (int m = 0; m < 4; ++m) { bf16_t* rowp = base + (size_t)(row0 + ai * HALF + m * 16) * ldc + col0;
;                 const float rs = rsv[ai][m];
; #pragma unroll
;                 for (int bj = 0; bj < 2; ++bj) { f32x4 v0 = acc[ai][bj][m][0], v1 = acc[ai][bj][m][1];
;                     if (RS) { v0 = v0 * rs; v1 = v1 * rs; }
;                     u32x4 w; w.x = cvt_pk_bf16(v0[0], v0[1]); w.y = cvt_pk_bf16(v0[2], v0[3]); w.z = cvt_pk_bf16(v1[0], v1[1]); w.w = cvt_pk_bf16(v1[2], v1[3]);
;                     *(u32x4*)(rowp + bj * HALF) = w; } }
; template <class Epi, class Sched, bool ALIGN_EPI = false, bool SP2 = false>
; __device__ __forceinline__ void gemm_phase(PG8_LAS unsigned char* lds, const Gemm g, const Sched& S, const Epi& E) {
;     ...
;         if constexpr (ALIGN_EPI) { if (wr == 0) PG8_BAR; }
;         if constexpr (!Epi::AFTER_DRAIN) { E(acc, cur, wr, wc, fr, fq); S.done(cur); }
;         if (!has_next) break;
; #pragma unroll
;         for (int a = 0; a < 2; ++a)
; #pragma unroll
;             for (int b = 0; b < 2; ++b)
; #pragma unroll
;                 for (int m = 0; m < 4; ++m)
; #pragma unroll
;                     for (int n = 0; n < 2; ++n) acc[a][b][m][n] = (f32x4){0.f, 0.f, 0.f, 0.f};
;         cur = nxt; cA = nA; cB = nB; ++ui;
;         if constexpr (ALIGN_EPI) { if (wr == 1) PG8_BAR; }
	v_cvt_pk_bf16_f32 v75, v78, v79
	global_store_dwordx4 v[84:85], v[72:75], off
	v_pk_mul_f32 v[68:69], v[68:69], v[170:171] op_sel_hi:[1,0]
	v_pk_mul_f32 v[60:61], v[60:61], v[174:175] op_sel_hi:[1,0]
	v_pk_mul_f32 v[72:73], v[66:67], v[170:171] op_sel_hi:[1,0]
	v_pk_mul_f32 v[66:67], v[64:65], v[170:171] op_sel_hi:[1,0]
	v_cvt_pk_bf16_f32 v64, v68, v69
	v_cvt_pk_bf16_f32 v65, v70, v71
	v_cvt_pk_bf16_f32 v66, v66, v67
	v_cvt_pk_bf16_f32 v67, v72, v73
	global_store_dwordx4 v[84:85], v[64:67], off offset:256
	v_pk_mul_f32 v[62:63], v[62:63], v[174:175] op_sel_hi:[1,0]
	v_pk_mul_f32 v[50:51], v[50:51], v[174:175] op_sel_hi:[1,0]
	v_pk_mul_f32 v[66:67], v[58:59], v[174:175] op_sel_hi:[1,0]
	v_pk_mul_f32 v[58:59], v[56:57], v[174:175] op_sel_hi:[1,0]
	v_cvt_pk_bf16_f32 v56, v60, v61
	v_add_co_u32_e32 v60, vcc, s17, v154
	v_cvt_pk_bf16_f32 v57, v62, v63
	v_cvt_pk_bf16_f32 v58, v58, v59
	v_cvt_pk_bf16_f32 v59, v66, v67
	v_addc_co_u32_e32 v61, vcc, 0, v155, vcc
	global_store_dwordx4 v[60:61], v[56:59], off
	v_pk_mul_f32 v[48:49], v[48:49], v[174:175] op_sel_hi:[1,0]
	v_lshl_add_u64 v[64:65], v[154:155], 0, s[24:25]
	v_pk_mul_f32 v[56:57], v[42:43], v[174:175] op_sel_hi:[1,0]
	v_pk_mul_f32 v[42:43], v[40:41], v[174:175] op_sel_hi:[1,0]
	v_cvt_pk_bf16_f32 v40, v48, v49
	v_cvt_pk_bf16_f32 v41, v50, v51
	v_cvt_pk_bf16_f32 v42, v42, v43
	v_cvt_pk_bf16_f32 v43, v56, v57
	global_store_dwordx4 v[64:65], v[40:43], off offset:256
	v_pk_mul_f32 v[44:45], v[44:45], v[176:177] op_sel_hi:[1,0]
	s_mov_b32 s17, 0x90000
	v_pk_mul_f32 v[42:43], v[54:55], v[176:177] op_sel_hi:[1,0]
	v_pk_mul_f32 v[40:41], v[52:53], v[176:177] op_sel_hi:[1,0]
	v_pk_mul_f32 v[46:47], v[46:47], v[176:177] op_sel_hi:[1,0]
	v_cvt_pk_bf16_f32 v40, v40, v41
	v_cvt_pk_bf16_f32 v41, v42, v43
	v_cvt_pk_bf16_f32 v42, v44, v45
	v_add_co_u32_e32 v44, vcc, s17, v154
	v_cvt_pk_bf16_f32 v43, v46, v47
	s_nop 0
	v_addc_co_u32_e32 v45, vcc, 0, v155, vcc
	global_store_dwordx4 v[44:45], v[40:43], off
	v_pk_mul_f32 v[34:35], v[34:35], v[176:177] op_sel_hi:[1,0]
	v_pk_mul_f32 v[32:33], v[32:33], v[176:177] op_sel_hi:[1,0]
	v_pk_mul_f32 v[40:41], v[26:27], v[176:177] op_sel_hi:[1,0]
	v_pk_mul_f32 v[26:27], v[24:25], v[176:177] op_sel_hi:[1,0]
	v_lshl_add_u64 v[48:49], v[154:155], 0, s[84:85]
	v_cvt_pk_bf16_f32 v24, v32, v33
	v_cvt_pk_bf16_f32 v25, v34, v35
	v_cvt_pk_bf16_f32 v26, v26, v27
	v_cvt_pk_bf16_f32 v27, v40, v41
	global_store_dwordx4 v[48:49], v[24:27], off offset:256
	v_pk_mul_f32 v[28:29], v[28:29], v[178:179] op_sel_hi:[1,0]
	s_mov_b32 s17, 0xa0000
	v_pk_mul_f32 v[26:27], v[38:39], v[178:179] op_sel_hi:[1,0]
	v_pk_mul_f32 v[24:25], v[36:37], v[178:179] op_sel_hi:[1,0]
	v_pk_mul_f32 v[30:31], v[30:31], v[178:179] op_sel_hi:[1,0]
	v_cvt_pk_bf16_f32 v24, v24, v25
	v_cvt_pk_bf16_f32 v25, v26, v27
	v_cvt_pk_bf16_f32 v26, v28, v29
	v_add_co_u32_e32 v28, vcc, s17, v154
	v_cvt_pk_bf16_f32 v27, v30, v31
	s_nop 0
	v_addc_co_u32_e32 v29, vcc, 0, v155, vcc
	global_store_dwordx4 v[28:29], v[24:27], off
	v_pk_mul_f32 v[18:19], v[18:19], v[178:179] op_sel_hi:[1,0]
	v_pk_mul_f32 v[16:17], v[16:17], v[178:179] op_sel_hi:[1,0]
	v_pk_mul_f32 v[24:25], v[10:11], v[178:179] op_sel_hi:[1,0]
	v_pk_mul_f32 v[10:11], v[8:9], v[178:179] op_sel_hi:[1,0]
	v_lshl_add_u64 v[32:33], v[154:155], 0, s[86:87]
	v_cvt_pk_bf16_f32 v8, v16, v17
	v_cvt_pk_bf16_f32 v9, v18, v19
	v_cvt_pk_bf16_f32 v10, v10, v11
	v_cvt_pk_bf16_f32 v11, v24, v25
	global_store_dwordx4 v[32:33], v[8:11], off offset:256
	v_pk_mul_f32 v[12:13], v[12:13], v[152:153] op_sel_hi:[1,0]
	s_mov_b32 s17, 0xb0000
	v_pk_mul_f32 v[10:11], v[22:23], v[152:153] op_sel_hi:[1,0]
	v_pk_mul_f32 v[8:9], v[20:21], v[152:153] op_sel_hi:[1,0]
	v_pk_mul_f32 v[14:15], v[14:15], v[152:153] op_sel_hi:[1,0]
	v_cvt_pk_bf16_f32 v8, v8, v9
	v_cvt_pk_bf16_f32 v9, v10, v11
	v_cvt_pk_bf16_f32 v10, v12, v13
	v_add_co_u32_e32 v12, vcc, s17, v154
	v_cvt_pk_bf16_f32 v11, v14, v15
	s_nop 0
	v_addc_co_u32_e32 v13, vcc, 0, v155, vcc
	global_store_dwordx4 v[12:13], v[8:11], off
	v_pk_mul_f32 v[6:7], v[6:7], v[152:153] op_sel_hi:[1,0]
	v_pk_mul_f32 v[4:5], v[4:5], v[152:153] op_sel_hi:[1,0]
	v_pk_mul_f32 v[8:9], v[2:3], v[152:153] op_sel_hi:[1,0]
	v_pk_mul_f32 v[2:3], v[0:1], v[152:153] op_sel_hi:[1,0]
	v_lshl_add_u64 v[16:17], v[154:155], 0, s[88:89]
	v_cvt_pk_bf16_f32 v0, v4, v5
	v_cvt_pk_bf16_f32 v1, v6, v7
	v_cvt_pk_bf16_f32 v2, v2, v3
	v_cvt_pk_bf16_f32 v3, v8, v9
	s_andn2_b64 vcc, exec, s[40:41]
	s_mov_b64 s[24:25], -1
	global_store_dwordx4 v[16:17], v[0:3], off offset:256
	s_cbranch_vccnz .LBB0_517
	s_andn2_b64 vcc, exec, s[10:11]
	s_cbranch_vccnz .LBB0_516
	s_barrier
	s_branch .LBB0_516

; #define G lgrid()
;     __host__ __device__ bool next(int i, Unit& u) const {
;         const long L = (long)i * G + c; if (L >= nwg) return false;
;         int wgid = (int)L; { const int q = nwg / NXCD, r = nwg % NXCD, xcd = wgid % NXCD, off = wgid / NXCD; wgid = (xcd < r ? xcd * (q + 1) : r * (q + 1) + (xcd - r) * q) + off; }
;         const int nig = WGM * nN, gid = wgid / nig, fm = gid * WGM, gsz = (nM - fm) < WGM ? (nM - fm) : WGM;
;         u.pm = fm + ((wgid % nig) % gsz); u.pn = (wgid % nig) / gsz; return true;
;     __device__ __forceinline__ void operator()(const f32x4 (&acc)[2][2][4][2], const Unit& u, int wr, int wc, int fr, int fq) const {
;     ...
;         for (int ai = 0; ai < 2; ++ai)
; #pragma unroll
;             for (int m = 0; m < 4; ++m) rsv[ai][m] = RS ? rs_of(SS, row0 + ai * HALF + m * 16) : 1.0f;
.LBB0_952:
	v_lshl_add_u32 v250, s28, 8, v153
	v_ashrrev_i32_e32 v251, 31, v250
	v_lshl_add_u64 v[252:253], v[250:251], 2, s[12:13]
	global_load_dword v242, v[252:253], off
	global_load_dword v243, v[252:253], off offset:64
	global_load_dword v244, v[252:253], off offset:128
	global_load_dword v245, v[252:253], off offset:192
	global_load_dword v246, v[252:253], off offset:512
	global_load_dword v247, v[252:253], off offset:576
	global_load_dword v248, v[252:253], off offset:640
	global_load_dword v249, v[252:253], off offset:704
	s_add_i32 s37, s37, 1
	s_mul_i32 s21, s37, s97
	s_mul_hi_u32 s23, s37, s96
	s_add_i32 s23, s23, s21
	s_mul_i32 s21, s37, s96
	s_add_u32 s24, s21, s44
	s_addc_u32 s25, s23, s45
	v_cmp_gt_i64_e32 vcc, s[24:25], v[214:215]
	v_cmp_lt_i64_e64 s[40:41], s[24:25], v[216:217]
	s_cbranch_vccnz .LBB0_954
	s_ashr_i32 s20, s24, 31
	s_lshr_b32 s20, s20, 29
	s_add_i32 s20, s24, s20
	s_ashr_i32 s21, s20, 3
	s_and_b32 s20, s20, -8
	s_sub_i32 s20, s24, s20
	s_cmp_lt_i32 s20, 0
	s_cselect_b32 s22, s33, 0x420
	s_mul_i32 s20, s20, s22
	s_add_i32 s20, s20, s21
	s_mul_hi_i32 s21, s20, 0x2e8ba2e9
	s_lshr_b32 s22, s21, 31
	s_ashr_i32 s21, s21, 5
	s_add_i32 s21, s21, s22
	s_lshl_b32 s22, s21, 2
	s_sub_i32 s23, 0xc0, s22
	s_min_i32 s23, s23, 4
	s_abs_i32 s24, s23
	v_cvt_f32_u32_e32 v0, s24
	s_sub_i32 s26, 0, s24
	s_mulk_i32 s21, 0xb0
	s_sub_i32 s21, s20, s21
	v_rcp_iflag_f32_e32 v0, v0
	s_abs_i32 s20, s21
	s_xor_b32 s25, s21, s23
	s_ashr_i32 s25, s25, 31
	v_mul_f32_e32 v0, 0x4f7ffffe, v0
	v_cvt_u32_f32_e32 v0, v0
	s_nop 0
	v_readfirstlane_b32 s27, v0
	s_mul_i32 s26, s26, s27
	s_mul_hi_u32 s26, s27, s26
	s_add_i32 s27, s27, s26
	s_mul_hi_u32 s26, s20, s27
	s_mul_i32 s27, s26, s24
	s_sub_i32 s20, s20, s27
	s_add_i32 s42, s26, 1
	s_sub_i32 s27, s20, s24
	s_cmp_ge_u32 s20, s24
	s_cselect_b32 s26, s42, s26
	s_cselect_b32 s20, s27, s20
	s_add_i32 s27, s26, 1
	s_cmp_ge_u32 s20, s24
	s_cselect_b32 s20, s27, s26
	s_xor_b32 s20, s20, s25
	s_sub_i32 s20, s20, s25
	s_mul_i32 s23, s20, s23
	s_sub_i32 s21, s21, s23
	s_add_i32 s22, s22, s21

; __device__ __forceinline__ unsigned cvt_pk_bf16(float lo, float hi) { f32x2c_t v = {lo, hi}; bf16x2c_t b = __builtin_convertvector(v, bf16x2c_t); return __builtin_bit_cast(unsigned, b); }
;     static __device__ __forceinline__ float sl(float g, float up) { return g * __builtin_amdgcn_rcpf(1.0f + __builtin_amdgcn_exp2f(-1.4426950408889634f * g)) * up; }
;     __device__ __forceinline__ void operator()(const f32x4 (&acc)[2][2][4][2], const Unit& u, int wr, int wc, int fr, int fq) const {
;         const int row0 = u.pm * BM + wr * 64 + fr; const int col0 = u.pn * HALF + wc * 32 + 8 * fq;
;         float rsv[2][4];
; #pragma unroll
;         for (int ai = 0; ai < 2; ++ai)
; #pragma unroll
;             for (int m = 0; m < 4; ++m) rsv[ai][m] = RS ? rs_of(SS, row0 + ai * HALF + m * 16) : 1.0f;
; #pragma unroll
;         for (int ai = 0; ai < 2; ++ai)
; #pragma unroll
;             for (int m = 0; m < 4; ++m) { bf16_t* rowp = O + (size_t)(row0 + ai * HALF + m * 16) * ldc + col0;
;                 f32x4 g0 = acc[ai][0][m][0], g1 = acc[ai][0][m][1], u0 = acc[ai][1][m][0], u1 = acc[ai][1][m][1];
;                 if (RS) { const float rs = rsv[ai][m]; g0 = g0 * rs; g1 = g1 * rs; u0 = u0 * rs; u1 = u1 * rs; }
;                 u32x4 w; w.x = cvt_pk_bf16(sl(g0[0], u0[0]), sl(g0[1], u0[1])); w.y = cvt_pk_bf16(sl(g0[2], u0[2]), sl(g0[3], u0[3]));
;                 w.z = cvt_pk_bf16(sl(g1[0], u1[0]), sl(g1[1], u1[1])); w.w = cvt_pk_bf16(sl(g1[2], u1[2]), sl(g1[3], u1[3]));
.LBB0_958:
	v_lshl_add_u32 v130, s28, 8, v153
	v_ashrrev_i32_e32 v131, 31, v130
	v_lshl_add_u64 v[132:133], v[130:131], 2, s[12:13]
	v_mov_b32_e32 v174, v242
	v_mov_b32_e32 v168, v243
	v_mov_b32_e32 v166, v244
	v_mov_b32_e32 v164, v245
	v_mov_b32_e32 v162, v246
	v_mov_b32_e32 v160, v247
	v_mov_b32_e32 v158, v248
	v_mov_b32_e32 v152, v249
	v_lshl_or_b32 v132, s29, 7, v161
	v_ashrrev_i32_e32 v133, 31, v132
	v_lshlrev_b64 v[156:157], 1, v[132:133]
	v_mov_b64_e32 v[154:155], s[16:17]
	v_or_b32_e32 v134, 16, v130
	v_or_b32_e32 v172, 32, v130
	v_or_b32_e32 v171, 48, v130
	v_add_u32_e32 v170, 0x80, v130
	v_add_u32_e32 v169, 0x90, v130
	v_add_u32_e32 v167, 0xa0, v130
	v_add_u32_e32 v165, 0xb0, v130
	v_mad_i64_i32 v[130:131], s[28:29], v130, s3, v[154:155]
	v_lshl_add_u64 v[130:131], v[130:131], 0, v[156:157]
	s_andn2_b64 vcc, exec, s[40:41]
	s_waitcnt vmcnt(8)
	v_pk_mul_f32 v[124:125], v[124:125], v[174:175] op_sel_hi:[1,0]
	v_pk_mul_f32 v[132:133], v[114:115], v[174:175] op_sel_hi:[1,0]
	v_pk_mul_f32 v[114:115], v[112:113], v[174:175] op_sel_hi:[1,0]
	v_mul_f32_e32 v112, 0xbfb8aa3b, v124
	v_mul_f32_e32 v113, 0xbfb8aa3b, v125
	v_exp_f32_e32 v112, v112
	v_exp_f32_e32 v113, v113
	v_pk_mul_f32 v[116:117], v[116:117], v[174:175] op_sel_hi:[1,0]
	v_pk_mul_f32 v[126:127], v[126:127], v[174:175] op_sel_hi:[1,0]
	v_add_f32_e32 v112, 1.0, v112
	v_add_f32_e32 v113, 1.0, v113
	v_rcp_f32_e32 v112, v112
	v_rcp_f32_e32 v113, v113
	v_pk_mul_f32 v[118:119], v[118:119], v[174:175] op_sel_hi:[1,0]
	v_pk_mul_f32 v[120:121], v[120:121], v[174:175] op_sel_hi:[1,0]
	v_pk_mul_f32 v[122:123], v[122:123], v[174:175] op_sel_hi:[1,0]
	v_pk_mul_f32 v[112:113], v[124:125], v[112:113]
	v_pk_mul_f32 v[108:109], v[108:109], v[168:169] op_sel_hi:[1,0]
	v_pk_mul_f32 v[112:113], v[116:117], v[112:113]
	v_pk_mul_f32 v[110:111], v[110:111], v[168:169] op_sel_hi:[1,0]
	v_cvt_pk_bf16_f32 v112, v112, v113
	v_mul_f32_e32 v113, 0xbfb8aa3b, v126
	v_exp_f32_e32 v113, v113
	v_pk_mul_f32 v[102:103], v[102:103], v[168:169] op_sel_hi:[1,0]
	v_pk_mul_f32 v[104:105], v[104:105], v[168:169] op_sel_hi:[1,0]
	v_pk_mul_f32 v[106:107], v[106:107], v[168:169] op_sel_hi:[1,0]
	v_add_f32_e32 v113, 1.0, v113
	v_rcp_f32_e32 v116, v113
	v_mul_f32_e32 v113, 0xbfb8aa3b, v127
	v_exp_f32_e32 v113, v113
	v_pk_mul_f32 v[92:93], v[92:93], v[166:167] op_sel_hi:[1,0]
	v_pk_mul_f32 v[84:85], v[84:85], v[166:167] op_sel_hi:[1,0]
	v_pk_mul_f32 v[94:95], v[94:95], v[166:167] op_sel_hi:[1,0]
	v_add_f32_e32 v113, 1.0, v113
	v_rcp_f32_e32 v117, v113
	v_pk_mul_f32 v[86:87], v[86:87], v[166:167] op_sel_hi:[1,0]
	v_pk_mul_f32 v[88:89], v[88:89], v[166:167] op_sel_hi:[1,0]
	v_pk_mul_f32 v[90:91], v[90:91], v[166:167] op_sel_hi:[1,0]
	v_pk_mul_f32 v[116:117], v[126:127], v[116:117]
	v_pk_mul_f32 v[76:77], v[76:77], v[164:165] op_sel_hi:[1,0]
	v_pk_mul_f32 v[116:117], v[118:119], v[116:117]
	v_pk_mul_f32 v[68:69], v[68:69], v[164:165] op_sel_hi:[1,0]
	v_cvt_pk_bf16_f32 v113, v116, v117
	v_mul_f32_e32 v116, 0xbfb8aa3b, v120
	v_mul_f32_e32 v117, 0xbfb8aa3b, v121
	v_exp_f32_e32 v116, v116
	v_exp_f32_e32 v117, v117
	v_pk_mul_f32 v[78:79], v[78:79], v[164:165] op_sel_hi:[1,0]
	v_pk_mul_f32 v[70:71], v[70:71], v[164:165] op_sel_hi:[1,0]
	v_add_f32_e32 v116, 1.0, v116
	v_add_f32_e32 v117, 1.0, v117
	v_rcp_f32_e32 v116, v116
	v_rcp_f32_e32 v117, v117
	v_pk_mul_f32 v[72:73], v[72:73], v[164:165] op_sel_hi:[1,0]
	v_pk_mul_f32 v[74:75], v[74:75], v[164:165] op_sel_hi:[1,0]
	v_pk_mul_f32 v[60:61], v[60:61], v[162:163] op_sel_hi:[1,0]
	v_pk_mul_f32 v[116:117], v[120:121], v[116:117]
	v_pk_mul_f32 v[52:53], v[52:53], v[162:163] op_sel_hi:[1,0]
	v_pk_mul_f32 v[114:115], v[114:115], v[116:117]
	v_pk_mul_f32 v[62:63], v[62:63], v[162:163] op_sel_hi:[1,0]
	v_cvt_pk_bf16_f32 v114, v114, v115
	v_mul_f32_e32 v115, 0xbfb8aa3b, v122
	v_exp_f32_e32 v115, v115
	v_pk_mul_f32 v[54:55], v[54:55], v[162:163] op_sel_hi:[1,0]
	v_pk_mul_f32 v[56:57], v[56:57], v[162:163] op_sel_hi:[1,0]
	v_pk_mul_f32 v[58:59], v[58:59], v[162:163] op_sel_hi:[1,0]
	v_add_f32_e32 v115, 1.0, v115
	v_rcp_f32_e32 v116, v115
	v_mul_f32_e32 v115, 0xbfb8aa3b, v123
	v_exp_f32_e32 v115, v115
	v_pk_mul_f32 v[44:45], v[44:45], v[160:161] op_sel_hi:[1,0]
	v_pk_mul_f32 v[36:37], v[36:37], v[160:161] op_sel_hi:[1,0]
	v_pk_mul_f32 v[46:47], v[46:47], v[160:161] op_sel_hi:[1,0]
	v_add_f32_e32 v115, 1.0, v115
	v_rcp_f32_e32 v117, v115
	v_pk_mul_f32 v[38:39], v[38:39], v[160:161] op_sel_hi:[1,0]
	v_pk_mul_f32 v[40:41], v[40:41], v[160:161] op_sel_hi:[1,0]
	v_pk_mul_f32 v[42:43], v[42:43], v[160:161] op_sel_hi:[1,0]
	v_pk_mul_f32 v[116:117], v[122:123], v[116:117]
	v_pk_mul_f32 v[28:29], v[28:29], v[158:159] op_sel_hi:[1,0]
	v_pk_mul_f32 v[116:117], v[132:133], v[116:117]
	v_pk_mul_f32 v[20:21], v[20:21], v[158:159] op_sel_hi:[1,0]
	v_cvt_pk_bf16_f32 v115, v116, v117
	global_store_dwordx4 v[130:131], v[112:115], off
	v_pk_mul_f32 v[30:31], v[30:31], v[158:159] op_sel_hi:[1,0]
	v_pk_mul_f32 v[22:23], v[22:23], v[158:159] op_sel_hi:[1,0]
	v_pk_mul_f32 v[114:115], v[100:101], v[168:169] op_sel_hi:[1,0]
	v_pk_mul_f32 v[100:101], v[98:99], v[168:169] op_sel_hi:[1,0]
	v_pk_mul_f32 v[98:99], v[96:97], v[168:169] op_sel_hi:[1,0]
	v_mul_f32_e32 v96, 0xbfb8aa3b, v108
	v_mul_f32_e32 v97, 0xbfb8aa3b, v109
	v_exp_f32_e32 v96, v96
	v_exp_f32_e32 v97, v97
	v_mad_i64_i32 v[112:113], s[28:29], v134, s3, v[154:155]
	v_add_f32_e32 v96, 1.0, v96
	v_add_f32_e32 v97, 1.0, v97
	v_rcp_f32_e32 v96, v96
	v_rcp_f32_e32 v97, v97
	v_lshl_add_u64 v[112:113], v[112:113], 0, v[156:157]
	v_pk_mul_f32 v[24:25], v[24:25], v[158:159] op_sel_hi:[1,0]
	v_pk_mul_f32 v[26:27], v[26:27], v[158:159] op_sel_hi:[1,0]
; __device__ __forceinline__ unsigned cvt_pk_bf16(float lo, float hi) { f32x2c_t v = {lo, hi}; bf16x2c_t b = __builtin_convertvector(v, bf16x2c_t); return __builtin_bit_cast(unsigned, b); }
;     static __device__ __forceinline__ float sl(float g, float up) { return g * __builtin_amdgcn_rcpf(1.0f + __builtin_amdgcn_exp2f(-1.4426950408889634f * g)) * up; }
;     __device__ __forceinline__ void operator()(const f32x4 (&acc)[2][2][4][2], const Unit& u, int wr, int wc, int fr, int fq) const {
;     ...
;             for (int m = 0; m < 4; ++m) { bf16_t* rowp = O + (size_t)(row0 + ai * HALF + m * 16) * ldc + col0;
;                 f32x4 g0 = acc[ai][0][m][0], g1 = acc[ai][0][m][1], u0 = acc[ai][1][m][0], u1 = acc[ai][1][m][1];
;                 if (RS) { const float rs = rsv[ai][m]; g0 = g0 * rs; g1 = g1 * rs; u0 = u0 * rs; u1 = u1 * rs; }
;                 u32x4 w; w.x = cvt_pk_bf16(sl(g0[0], u0[0]), sl(g0[1], u0[1])); w.y = cvt_pk_bf16(sl(g0[2], u0[2]), sl(g0[3], u0[3]));
;                 w.z = cvt_pk_bf16(sl(g1[0], u1[0]), sl(g1[1], u1[1])); w.w = cvt_pk_bf16(sl(g1[2], u1[2]), sl(g1[3], u1[3]));
;                 *(u32x4*)rowp = w; }
	v_pk_mul_f32 v[96:97], v[108:109], v[96:97]
	v_pk_mul_f32 v[12:13], v[12:13], v[152:153] op_sel_hi:[1,0]
	v_pk_mul_f32 v[96:97], v[114:115], v[96:97]
	v_pk_mul_f32 v[4:5], v[4:5], v[152:153] op_sel_hi:[1,0]
	v_cvt_pk_bf16_f32 v96, v96, v97
	v_mul_f32_e32 v97, 0xbfb8aa3b, v110
	v_exp_f32_e32 v97, v97
	v_pk_mul_f32 v[14:15], v[14:15], v[152:153] op_sel_hi:[1,0]
	v_pk_mul_f32 v[6:7], v[6:7], v[152:153] op_sel_hi:[1,0]
	v_pk_mul_f32 v[8:9], v[8:9], v[152:153] op_sel_hi:[1,0]
	v_add_f32_e32 v97, 1.0, v97
	v_rcp_f32_e32 v108, v97
	v_mul_f32_e32 v97, 0xbfb8aa3b, v111
	v_exp_f32_e32 v97, v97
	v_pk_mul_f32 v[10:11], v[10:11], v[152:153] op_sel_hi:[1,0]
	v_add_f32_e32 v97, 1.0, v97
	v_rcp_f32_e32 v109, v97
	s_nop 0
	v_pk_mul_f32 v[108:109], v[110:111], v[108:109]
	s_nop 0
	v_pk_mul_f32 v[102:103], v[102:103], v[108:109]
	s_nop 0
	v_cvt_pk_bf16_f32 v97, v102, v103
	v_mul_f32_e32 v102, 0xbfb8aa3b, v104
	v_mul_f32_e32 v103, 0xbfb8aa3b, v105
	v_exp_f32_e32 v102, v102
	v_exp_f32_e32 v103, v103
	v_add_f32_e32 v102, 1.0, v102
	v_add_f32_e32 v103, 1.0, v103
	v_rcp_f32_e32 v102, v102
	v_rcp_f32_e32 v103, v103
	s_nop 0
	v_pk_mul_f32 v[102:103], v[104:105], v[102:103]
	s_nop 0
	v_pk_mul_f32 v[98:99], v[98:99], v[102:103]
	s_nop 0
	v_cvt_pk_bf16_f32 v98, v98, v99
	v_mul_f32_e32 v99, 0xbfb8aa3b, v106
	v_exp_f32_e32 v99, v99
	s_nop 0
	v_add_f32_e32 v99, 1.0, v99
	v_rcp_f32_e32 v102, v99
	v_mul_f32_e32 v99, 0xbfb8aa3b, v107
	v_exp_f32_e32 v99, v99
	s_nop 0
	v_add_f32_e32 v99, 1.0, v99
	v_rcp_f32_e32 v103, v99
	s_nop 0
	v_pk_mul_f32 v[102:103], v[106:107], v[102:103]
	s_nop 0
	v_pk_mul_f32 v[100:101], v[100:101], v[102:103]
	s_nop 0
	v_cvt_pk_bf16_f32 v99, v100, v101
	global_store_dwordx4 v[112:113], v[96:99], off
	s_nop 1
	v_pk_mul_f32 v[98:99], v[82:83], v[166:167] op_sel_hi:[1,0]
	v_pk_mul_f32 v[82:83], v[80:81], v[166:167] op_sel_hi:[1,0]
	v_mul_f32_e32 v80, 0xbfb8aa3b, v92
	v_mul_f32_e32 v81, 0xbfb8aa3b, v93
	v_exp_f32_e32 v80, v80
	v_exp_f32_e32 v81, v81
	v_mad_i64_i32 v[96:97], s[28:29], v172, s3, v[154:155]
	v_add_f32_e32 v80, 1.0, v80
	v_add_f32_e32 v81, 1.0, v81
	v_rcp_f32_e32 v80, v80
	v_rcp_f32_e32 v81, v81
	v_lshl_add_u64 v[96:97], v[96:97], 0, v[156:157]
	v_pk_mul_f32 v[80:81], v[92:93], v[80:81]
	s_nop 0
	v_pk_mul_f32 v[80:81], v[84:85], v[80:81]
	s_nop 0
	v_cvt_pk_bf16_f32 v80, v80, v81
	v_mul_f32_e32 v81, 0xbfb8aa3b, v94
	v_exp_f32_e32 v81, v81
	s_nop 0
	v_add_f32_e32 v81, 1.0, v81
	v_rcp_f32_e32 v84, v81
	v_mul_f32_e32 v81, 0xbfb8aa3b, v95
	v_exp_f32_e32 v81, v81
	s_nop 0
	v_add_f32_e32 v81, 1.0, v81
	v_rcp_f32_e32 v85, v81
	s_nop 0
	v_pk_mul_f32 v[84:85], v[94:95], v[84:85]
	s_nop 0
	v_pk_mul_f32 v[84:85], v[86:87], v[84:85]
	s_nop 0
	v_cvt_pk_bf16_f32 v81, v84, v85
	v_mul_f32_e32 v84, 0xbfb8aa3b, v88
	v_mul_f32_e32 v85, 0xbfb8aa3b, v89
	v_exp_f32_e32 v84, v84
	v_exp_f32_e32 v85, v85
	v_add_f32_e32 v84, 1.0, v84
	v_add_f32_e32 v85, 1.0, v85
	v_rcp_f32_e32 v84, v84
	v_rcp_f32_e32 v85, v85
	s_nop 0
	v_pk_mul_f32 v[84:85], v[88:89], v[84:85]
	s_nop 0
	v_pk_mul_f32 v[82:83], v[82:83], v[84:85]
	s_nop 0
	v_cvt_pk_bf16_f32 v82, v82, v83
	v_mul_f32_e32 v83, 0xbfb8aa3b, v90
	v_exp_f32_e32 v83, v83
	s_nop 0
	v_add_f32_e32 v83, 1.0, v83
	v_rcp_f32_e32 v84, v83
	v_mul_f32_e32 v83, 0xbfb8aa3b, v91
	v_exp_f32_e32 v83, v83
	s_nop 0
	v_add_f32_e32 v83, 1.0, v83
	v_rcp_f32_e32 v85, v83
	s_nop 0
	v_pk_mul_f32 v[84:85], v[90:91], v[84:85]
	s_nop 0
	v_pk_mul_f32 v[84:85], v[98:99], v[84:85]
	s_nop 0
	v_cvt_pk_bf16_f32 v83, v84, v85
	global_store_dwordx4 v[96:97], v[80:83], off
	s_nop 1
	v_pk_mul_f32 v[82:83], v[66:67], v[164:165] op_sel_hi:[1,0]
	v_pk_mul_f32 v[66:67], v[64:65], v[164:165] op_sel_hi:[1,0]
	v_mul_f32_e32 v64, 0xbfb8aa3b, v76
	v_mul_f32_e32 v65, 0xbfb8aa3b, v77
	v_exp_f32_e32 v64, v64
	v_exp_f32_e32 v65, v65
	v_mad_i64_i32 v[80:81], s[28:29], v171, s3, v[154:155]
	v_add_f32_e32 v64, 1.0, v64
	v_add_f32_e32 v65, 1.0, v65
	v_rcp_f32_e32 v64, v64
	v_rcp_f32_e32 v65, v65
	v_lshl_add_u64 v[80:81], v[80:81], 0, v[156:157]
	v_pk_mul_f32 v[64:65], v[76:77], v[64:65]
	s_nop 0
	v_pk_mul_f32 v[64:65], v[68:69], v[64:65]
	s_nop 0
	v_cvt_pk_bf16_f32 v64, v64, v65
	v_mul_f32_e32 v65, 0xbfb8aa3b, v78
	v_exp_f32_e32 v65, v65
	s_nop 0
	v_add_f32_e32 v65, 1.0, v65
	v_rcp_f32_e32 v68, v65
	v_mul_f32_e32 v65, 0xbfb8aa3b, v79
	v_exp_f32_e32 v65, v65
	s_nop 0
	v_add_f32_e32 v65, 1.0, v65
	v_rcp_f32_e32 v69, v65
	s_nop 0
	v_pk_mul_f32 v[68:69], v[78:79], v[68:69]
	s_nop 0
	v_pk_mul_f32 v[68:69], v[70:71], v[68:69]
	s_nop 0
	v_cvt_pk_bf16_f32 v65, v68, v69
	v_mul_f32_e32 v68, 0xbfb8aa3b, v72
	v_mul_f32_e32 v69, 0xbfb8aa3b, v73
	v_exp_f32_e32 v68, v68
	v_exp_f32_e32 v69, v69
	v_add_f32_e32 v68, 1.0, v68
	v_add_f32_e32 v69, 1.0, v69
	v_rcp_f32_e32 v68, v68
	v_rcp_f32_e32 v69, v69
	s_nop 0
	v_pk_mul_f32 v[68:69], v[72:73], v[68:69]
	s_nop 0
	v_pk_mul_f32 v[66:67], v[66:67], v[68:69]
	s_nop 0
	v_cvt_pk_bf16_f32 v66, v66, v67
	v_mul_f32_e32 v67, 0xbfb8aa3b, v74
	v_exp_f32_e32 v67, v67
	s_nop 0
	v_add_f32_e32 v67, 1.0, v67
	v_rcp_f32_e32 v68, v67
	v_mul_f32_e32 v67, 0xbfb8aa3b, v75
	v_exp_f32_e32 v67, v67
	s_nop 0
	v_add_f32_e32 v67, 1.0, v67
	v_rcp_f32_e32 v69, v67
	s_nop 0
	v_pk_mul_f32 v[68:69], v[74:75], v[68:69]
	s_nop 0
	v_pk_mul_f32 v[68:69], v[82:83], v[68:69]
	s_nop 0
	v_cvt_pk_bf16_f32 v67, v68, v69
	global_store_dwordx4 v[80:81], v[64:67], off
	s_nop 1
	v_pk_mul_f32 v[66:67], v[50:51], v[162:163] op_sel_hi:[1,0]
	v_pk_mul_f32 v[50:51], v[48:49], v[162:163] op_sel_hi:[1,0]
	v_mul_f32_e32 v48, 0xbfb8aa3b, v60
	v_mul_f32_e32 v49, 0xbfb8aa3b, v61
	v_exp_f32_e32 v48, v48
	v_exp_f32_e32 v49, v49
	v_mad_i64_i32 v[64:65], s[28:29], v170, s3, v[154:155]
	v_add_f32_e32 v48, 1.0, v48
; __device__ __forceinline__ unsigned cvt_pk_bf16(float lo, float hi) { f32x2c_t v = {lo, hi}; bf16x2c_t b = __builtin_convertvector(v, bf16x2c_t); return __builtin_bit_cast(unsigned, b); }
;     static __device__ __forceinline__ float sl(float g, float up) { return g * __builtin_amdgcn_rcpf(1.0f + __builtin_amdgcn_exp2f(-1.4426950408889634f * g)) * up; }
; #define PG8_BAR __builtin_amdgcn_s_barrier()
;     __device__ __forceinline__ void operator()(const f32x4 (&acc)[2][2][4][2], const Unit& u, int wr, int wc, int fr, int fq) const {
;     ...
;             for (int m = 0; m < 4; ++m) { bf16_t* rowp = O + (size_t)(row0 + ai * HALF + m * 16) * ldc + col0;
;                 f32x4 g0 = acc[ai][0][m][0], g1 = acc[ai][0][m][1], u0 = acc[ai][1][m][0], u1 = acc[ai][1][m][1];
;                 if (RS) { const float rs = rsv[ai][m]; g0 = g0 * rs; g1 = g1 * rs; u0 = u0 * rs; u1 = u1 * rs; }
;                 u32x4 w; w.x = cvt_pk_bf16(sl(g0[0], u0[0]), sl(g0[1], u0[1])); w.y = cvt_pk_bf16(sl(g0[2], u0[2]), sl(g0[3], u0[3]));
;                 w.z = cvt_pk_bf16(sl(g1[0], u1[0]), sl(g1[1], u1[1])); w.w = cvt_pk_bf16(sl(g1[2], u1[2]), sl(g1[3], u1[3]));
;                 *(u32x4*)rowp = w; }
; template <class Epi, class Sched, bool ALIGN_EPI = false, bool SP2 = false>
; __device__ __forceinline__ void gemm_phase(PG8_LAS unsigned char* lds, const Gemm g, const Sched& S, const Epi& E) {
;     ...
;         if constexpr (ALIGN_EPI) { if (wr == 0) PG8_BAR; }
;         if constexpr (!Epi::AFTER_DRAIN) { E(acc, cur, wr, wc, fr, fq); S.done(cur); }
;         if (!has_next) break;
; #pragma unroll
;         for (int a = 0; a < 2; ++a)
; #pragma unroll
;             for (int b = 0; b < 2; ++b)
; #pragma unroll
;                 for (int m = 0; m < 4; ++m)
; #pragma unroll
;                     for (int n = 0; n < 2; ++n) acc[a][b][m][n] = (f32x4){0.f, 0.f, 0.f, 0.f};
;         cur = nxt; cA = nA; cB = nB; ++ui;
;         if constexpr (ALIGN_EPI) { if (wr == 1) PG8_BAR; }
	v_add_f32_e32 v49, 1.0, v49
	v_rcp_f32_e32 v48, v48
	v_rcp_f32_e32 v49, v49
	v_lshl_add_u64 v[64:65], v[64:65], 0, v[156:157]
	v_pk_mul_f32 v[48:49], v[60:61], v[48:49]
	s_nop 0
	v_pk_mul_f32 v[48:49], v[52:53], v[48:49]
	s_nop 0
	v_cvt_pk_bf16_f32 v48, v48, v49
	v_mul_f32_e32 v49, 0xbfb8aa3b, v62
	v_exp_f32_e32 v49, v49
	s_nop 0
	v_add_f32_e32 v49, 1.0, v49
	v_rcp_f32_e32 v52, v49
	v_mul_f32_e32 v49, 0xbfb8aa3b, v63
	v_exp_f32_e32 v49, v49
	s_nop 0
	v_add_f32_e32 v49, 1.0, v49
	v_rcp_f32_e32 v53, v49
	s_nop 0
	v_pk_mul_f32 v[52:53], v[62:63], v[52:53]
	s_nop 0
	v_pk_mul_f32 v[52:53], v[54:55], v[52:53]
	s_nop 0
	v_cvt_pk_bf16_f32 v49, v52, v53
	v_mul_f32_e32 v52, 0xbfb8aa3b, v56
	v_mul_f32_e32 v53, 0xbfb8aa3b, v57
	v_exp_f32_e32 v52, v52
	v_exp_f32_e32 v53, v53
	v_add_f32_e32 v52, 1.0, v52
	v_add_f32_e32 v53, 1.0, v53
	v_rcp_f32_e32 v52, v52
	v_rcp_f32_e32 v53, v53
	s_nop 0
	v_pk_mul_f32 v[52:53], v[56:57], v[52:53]
	s_nop 0
	v_pk_mul_f32 v[50:51], v[50:51], v[52:53]
	s_nop 0
	v_cvt_pk_bf16_f32 v50, v50, v51
	v_mul_f32_e32 v51, 0xbfb8aa3b, v58
	v_exp_f32_e32 v51, v51
	s_nop 0
	v_add_f32_e32 v51, 1.0, v51
	v_rcp_f32_e32 v52, v51
	v_mul_f32_e32 v51, 0xbfb8aa3b, v59
	v_exp_f32_e32 v51, v51
	s_nop 0
	v_add_f32_e32 v51, 1.0, v51
	v_rcp_f32_e32 v53, v51
	s_nop 0
	v_pk_mul_f32 v[52:53], v[58:59], v[52:53]
	s_nop 0
	v_pk_mul_f32 v[52:53], v[66:67], v[52:53]
	s_nop 0
	v_cvt_pk_bf16_f32 v51, v52, v53
	global_store_dwordx4 v[64:65], v[48:51], off
	s_nop 1
	v_pk_mul_f32 v[50:51], v[34:35], v[160:161] op_sel_hi:[1,0]
	v_pk_mul_f32 v[34:35], v[32:33], v[160:161] op_sel_hi:[1,0]
	v_mul_f32_e32 v32, 0xbfb8aa3b, v44
	v_mul_f32_e32 v33, 0xbfb8aa3b, v45
	v_exp_f32_e32 v32, v32
	v_exp_f32_e32 v33, v33
	v_mad_i64_i32 v[48:49], s[28:29], v169, s3, v[154:155]
	v_add_f32_e32 v32, 1.0, v32
	v_add_f32_e32 v33, 1.0, v33
	v_rcp_f32_e32 v32, v32
	v_rcp_f32_e32 v33, v33
	v_lshl_add_u64 v[48:49], v[48:49], 0, v[156:157]
	v_pk_mul_f32 v[32:33], v[44:45], v[32:33]
	s_nop 0
	v_pk_mul_f32 v[32:33], v[36:37], v[32:33]
	s_nop 0
	v_cvt_pk_bf16_f32 v32, v32, v33
	v_mul_f32_e32 v33, 0xbfb8aa3b, v46
	v_exp_f32_e32 v33, v33
	s_nop 0
	v_add_f32_e32 v33, 1.0, v33
	v_rcp_f32_e32 v36, v33
	v_mul_f32_e32 v33, 0xbfb8aa3b, v47
	v_exp_f32_e32 v33, v33
	s_nop 0
	v_add_f32_e32 v33, 1.0, v33
	v_rcp_f32_e32 v37, v33
	s_nop 0
	v_pk_mul_f32 v[36:37], v[46:47], v[36:37]
	s_nop 0
	v_pk_mul_f32 v[36:37], v[38:39], v[36:37]
	s_nop 0
	v_cvt_pk_bf16_f32 v33, v36, v37
	v_mul_f32_e32 v36, 0xbfb8aa3b, v40
	v_mul_f32_e32 v37, 0xbfb8aa3b, v41
	v_exp_f32_e32 v36, v36
	v_exp_f32_e32 v37, v37
	v_add_f32_e32 v36, 1.0, v36
	v_add_f32_e32 v37, 1.0, v37
	v_rcp_f32_e32 v36, v36
	v_rcp_f32_e32 v37, v37
	s_nop 0
	v_pk_mul_f32 v[36:37], v[40:41], v[36:37]
	s_nop 0
	v_pk_mul_f32 v[34:35], v[34:35], v[36:37]
	s_nop 0
	v_cvt_pk_bf16_f32 v34, v34, v35
	v_mul_f32_e32 v35, 0xbfb8aa3b, v42
	v_exp_f32_e32 v35, v35
	s_nop 0
	v_add_f32_e32 v35, 1.0, v35
	v_rcp_f32_e32 v36, v35
	v_mul_f32_e32 v35, 0xbfb8aa3b, v43
	v_exp_f32_e32 v35, v35
	s_nop 0
	v_add_f32_e32 v35, 1.0, v35
	v_rcp_f32_e32 v37, v35
	s_nop 0
	v_pk_mul_f32 v[36:37], v[42:43], v[36:37]
	s_nop 0
	v_pk_mul_f32 v[36:37], v[50:51], v[36:37]
	s_nop 0
	v_cvt_pk_bf16_f32 v35, v36, v37
	global_store_dwordx4 v[48:49], v[32:35], off
	s_nop 1
	v_pk_mul_f32 v[34:35], v[18:19], v[158:159] op_sel_hi:[1,0]
	v_pk_mul_f32 v[18:19], v[16:17], v[158:159] op_sel_hi:[1,0]
	v_mul_f32_e32 v16, 0xbfb8aa3b, v28
	v_mul_f32_e32 v17, 0xbfb8aa3b, v29
	v_exp_f32_e32 v16, v16
	v_exp_f32_e32 v17, v17
	v_mad_i64_i32 v[32:33], s[28:29], v167, s3, v[154:155]
	v_add_f32_e32 v16, 1.0, v16
	v_add_f32_e32 v17, 1.0, v17
	v_rcp_f32_e32 v16, v16
	v_rcp_f32_e32 v17, v17
	v_lshl_add_u64 v[32:33], v[32:33], 0, v[156:157]
	v_pk_mul_f32 v[16:17], v[28:29], v[16:17]
	s_nop 0
	v_pk_mul_f32 v[16:17], v[20:21], v[16:17]
	s_nop 0
	v_cvt_pk_bf16_f32 v16, v16, v17
	v_mul_f32_e32 v17, 0xbfb8aa3b, v30
	v_exp_f32_e32 v17, v17
	s_nop 0
	v_add_f32_e32 v17, 1.0, v17
	v_rcp_f32_e32 v20, v17
	v_mul_f32_e32 v17, 0xbfb8aa3b, v31
	v_exp_f32_e32 v17, v17
	s_nop 0
	v_add_f32_e32 v17, 1.0, v17
	v_rcp_f32_e32 v21, v17
	s_nop 0
	v_pk_mul_f32 v[20:21], v[30:31], v[20:21]
	s_nop 0
	v_pk_mul_f32 v[20:21], v[22:23], v[20:21]
	s_nop 0
	v_cvt_pk_bf16_f32 v17, v20, v21
	v_mul_f32_e32 v20, 0xbfb8aa3b, v24
	v_mul_f32_e32 v21, 0xbfb8aa3b, v25
	v_exp_f32_e32 v20, v20
	v_exp_f32_e32 v21, v21
	v_add_f32_e32 v20, 1.0, v20
	v_add_f32_e32 v21, 1.0, v21
	v_rcp_f32_e32 v20, v20
	v_rcp_f32_e32 v21, v21
	s_nop 0
	v_pk_mul_f32 v[20:21], v[24:25], v[20:21]
	s_nop 0
	v_pk_mul_f32 v[18:19], v[18:19], v[20:21]
	s_nop 0
	v_cvt_pk_bf16_f32 v18, v18, v19
	v_mul_f32_e32 v19, 0xbfb8aa3b, v26
	v_exp_f32_e32 v19, v19
	s_nop 0
	v_add_f32_e32 v19, 1.0, v19
	v_rcp_f32_e32 v20, v19
	v_mul_f32_e32 v19, 0xbfb8aa3b, v27
	v_exp_f32_e32 v19, v19
	s_nop 0
	v_add_f32_e32 v19, 1.0, v19
	v_rcp_f32_e32 v21, v19
	s_nop 0
	v_pk_mul_f32 v[20:21], v[26:27], v[20:21]
	s_nop 0
	v_pk_mul_f32 v[20:21], v[34:35], v[20:21]
	s_nop 0
	v_cvt_pk_bf16_f32 v19, v20, v21
	global_store_dwordx4 v[32:33], v[16:19], off
	s_nop 1
	v_pk_mul_f32 v[18:19], v[2:3], v[152:153] op_sel_hi:[1,0]
	v_pk_mul_f32 v[2:3], v[0:1], v[152:153] op_sel_hi:[1,0]
	v_mul_f32_e32 v0, 0xbfb8aa3b, v12
	v_mul_f32_e32 v1, 0xbfb8aa3b, v13
	v_exp_f32_e32 v0, v0
	v_exp_f32_e32 v1, v1
	v_mad_i64_i32 v[16:17], s[28:29], v165, s3, v[154:155]
	v_add_f32_e32 v0, 1.0, v0
	v_add_f32_e32 v1, 1.0, v1
	v_rcp_f32_e32 v0, v0
	v_rcp_f32_e32 v1, v1
	v_lshl_add_u64 v[16:17], v[16:17], 0, v[156:157]
	s_mov_b64 s[28:29], -1
	v_pk_mul_f32 v[0:1], v[12:13], v[0:1]
	s_nop 0
	v_pk_mul_f32 v[0:1], v[4:5], v[0:1]
	s_nop 0
	v_cvt_pk_bf16_f32 v0, v0, v1
	v_mul_f32_e32 v1, 0xbfb8aa3b, v14
	v_exp_f32_e32 v1, v1
	s_nop 0
	v_add_f32_e32 v1, 1.0, v1
	v_rcp_f32_e32 v4, v1
	v_mul_f32_e32 v1, 0xbfb8aa3b, v15
	v_exp_f32_e32 v1, v1
	s_nop 0
	v_add_f32_e32 v1, 1.0, v1
	v_rcp_f32_e32 v5, v1
	s_nop 0
	v_pk_mul_f32 v[4:5], v[14:15], v[4:5]
	s_nop 0
	v_pk_mul_f32 v[4:5], v[6:7], v[4:5]
	s_nop 0
	v_cvt_pk_bf16_f32 v1, v4, v5
	v_mul_f32_e32 v4, 0xbfb8aa3b, v8
	v_mul_f32_e32 v5, 0xbfb8aa3b, v9
	v_exp_f32_e32 v4, v4
	v_exp_f32_e32 v5, v5
	v_add_f32_e32 v4, 1.0, v4
	v_add_f32_e32 v5, 1.0, v5
	v_rcp_f32_e32 v4, v4
	v_rcp_f32_e32 v5, v5
	s_nop 0
	v_pk_mul_f32 v[4:5], v[8:9], v[4:5]
	s_nop 0
	v_pk_mul_f32 v[2:3], v[2:3], v[4:5]
	s_nop 0
	v_cvt_pk_bf16_f32 v2, v2, v3
	v_mul_f32_e32 v3, 0xbfb8aa3b, v10
	v_exp_f32_e32 v3, v3
	s_nop 0
	v_add_f32_e32 v3, 1.0, v3
	v_rcp_f32_e32 v4, v3
	v_mul_f32_e32 v3, 0xbfb8aa3b, v11
	v_exp_f32_e32 v3, v3
	s_nop 0
	v_add_f32_e32 v3, 1.0, v3
	v_rcp_f32_e32 v5, v3
	s_nop 0
	v_pk_mul_f32 v[4:5], v[10:11], v[4:5]
	s_nop 0
	v_pk_mul_f32 v[4:5], v[18:19], v[4:5]
	s_nop 0
	v_cvt_pk_bf16_f32 v3, v4, v5
	global_store_dwordx4 v[16:17], v[0:3], off
	s_cbranch_vccnz .LBB0_951
	s_andn2_b64 vcc, exec, s[14:15]
	s_cbranch_vccnz .LBB0_950
	s_barrier
	s_branch .LBB0_950

; #define G lgrid()
;     __host__ __device__ bool next(int i, Unit& u) const {
;         const long L = (long)i * G + c; if (L >= nwg) return false;
;         int wgid = (int)L; { const int q = nwg / NXCD, r = nwg % NXCD, xcd = wgid % NXCD, off = wgid / NXCD; wgid = (xcd < r ? xcd * (q + 1) : r * (q + 1) + (xcd - r) * q) + off; }
;         const int nig = WGM * nN, gid = wgid / nig, fm = gid * WGM, gsz = (nM - fm) < WGM ? (nM - fm) : WGM;
;         u.pm = fm + ((wgid % nig) % gsz); u.pn = (wgid % nig) / gsz; return true;
;     __device__ __forceinline__ void operator()(const f32x4 (&acc)[2][2][4][2], const Unit& u, int wr, int wc, int fr, int fq) const {
;     ...
;             for (int m = 0; m < 4; ++m) rsv[ai][m] = RS ? rs_of(SS, row0 + ai * HALF + m * 16) : 1.0f;
.LBB0_1119:
	v_lshl_add_u32 v250, s28, 8, v153
	v_ashrrev_i32_e32 v251, 31, v250
	v_lshl_add_u64 v[252:253], v[250:251], 2, s[6:7]
	global_load_dword v242, v[252:253], off
	global_load_dword v243, v[252:253], off offset:64
	global_load_dword v244, v[252:253], off offset:128
	global_load_dword v245, v[252:253], off offset:192
	global_load_dword v246, v[252:253], off offset:512
	global_load_dword v247, v[252:253], off offset:576
	global_load_dword v248, v[252:253], off offset:640
	global_load_dword v249, v[252:253], off offset:704
	s_add_i32 s60, s60, 1
	s_mul_i32 s21, s60, s37
	s_mul_hi_u32 s23, s60, s36
	s_add_i32 s23, s23, s21
	s_mul_i32 s21, s60, s36
	s_add_u32 s24, s21, s12
	s_addc_u32 s25, s23, s13
	v_cmp_gt_i64_e32 vcc, s[24:25], v[240:241]
	v_cmp_lt_i64_e64 s[40:41], s[24:25], v[210:211]
	s_cbranch_vccnz .LBB0_1121
	s_ashr_i32 s20, s24, 31
	s_lshr_b32 s20, s20, 29
	s_add_i32 s20, s24, s20
	s_ashr_i32 s21, s20, 3
	s_and_b32 s20, s20, -8
	s_sub_i32 s20, s24, s20
	s_cmp_lt_i32 s20, 0
	s_cselect_b32 s22, s63, 0xc0
	s_mul_i32 s20, s20, s22
	s_add_i32 s20, s20, s21
	s_ashr_i32 s21, s20, 31
	s_lshr_b32 s21, s21, 27
	s_add_i32 s21, s20, s21
	s_ashr_i32 s22, s21, 5
	s_lshl_b32 s22, s22, 2
	s_sub_i32 s23, 0xc0, s22
	s_min_i32 s23, s23, 4
	s_abs_i32 s24, s23
	v_cvt_f32_u32_e32 v0, s24
	s_sub_i32 s26, 0, s24
	s_andn2_b32 s21, s21, 31
	s_sub_i32 s21, s20, s21
	v_rcp_iflag_f32_e32 v0, v0
	s_abs_i32 s20, s21
	s_xor_b32 s25, s21, s23
	s_ashr_i32 s25, s25, 31
	v_mul_f32_e32 v0, 0x4f7ffffe, v0
	v_cvt_u32_f32_e32 v0, v0
	s_nop 0
	v_readfirstlane_b32 s27, v0
	s_mul_i32 s26, s26, s27
	s_mul_hi_u32 s26, s27, s26
	s_add_i32 s27, s27, s26
	s_mul_hi_u32 s26, s20, s27
	s_mul_i32 s27, s26, s24
	s_sub_i32 s20, s20, s27
	s_add_i32 s42, s26, 1
	s_sub_i32 s27, s20, s24
	s_cmp_ge_u32 s20, s24
	s_cselect_b32 s26, s42, s26
	s_cselect_b32 s20, s27, s20
	s_add_i32 s27, s26, 1
	s_cmp_ge_u32 s20, s24
	s_cselect_b32 s20, s27, s26
	s_xor_b32 s20, s20, s25
	s_sub_i32 s20, s20, s25
	s_mul_i32 s23, s20, s23
	s_sub_i32 s21, s21, s23
	s_add_i32 s22, s22, s21

; __device__ __forceinline__ unsigned cvt_pk_bf16(float lo, float hi) { f32x2c_t v = {lo, hi}; bf16x2c_t b = __builtin_convertvector(v, bf16x2c_t); return __builtin_bit_cast(unsigned, b); }
;     static __device__ __forceinline__ float sg(float x) { return __builtin_amdgcn_rcpf(1.0f + __builtin_amdgcn_exp2f(-1.4426950408889634f * x)); }
;     __device__ __forceinline__ void operator()(const f32x4 (&acc)[2][2][4][2], const Unit& u, int wr, int wc, int fr, int fq) const {
;         const int row0 = u.pm * BM + wr * 64 + fr; const int col0 = u.pn * BM + wc * 32 + 8 * fq;
;         float rsv[2][4];
; #pragma unroll
;         for (int ai = 0; ai < 2; ++ai)
; #pragma unroll
;             for (int m = 0; m < 4; ++m) rsv[ai][m] = RS ? rs_of(SS, row0 + ai * HALF + m * 16) : 1.0f;
; #pragma unroll
;         for (int ai = 0; ai < 2; ++ai)
; #pragma unroll
;             for (int m = 0; m < 4; ++m) { bf16_t* rowp = O + (size_t)(row0 + ai * HALF + m * 16) * ldc + col0;
;                 const float rs = rsv[ai][m];
; #pragma unroll
;                 for (int bj = 0; bj < 2; ++bj) { f32x4 v0 = acc[ai][bj][m][0], v1 = acc[ai][bj][m][1];
;                     if (RS) { v0 = v0 * rs; v1 = v1 * rs; }
;                     u32x4 w; w.x = cvt_pk_bf16(sg(v0[0]), sg(v0[1])); w.y = cvt_pk_bf16(sg(v0[2]), sg(v0[3])); w.z = cvt_pk_bf16(sg(v1[0]), sg(v1[1])); w.w = cvt_pk_bf16(sg(v1[2]), sg(v1[3]));
;                     *(u32x4*)(rowp + bj * HALF) = w; } }
.LBB0_1125:
	v_lshl_add_u32 v130, s28, 8, v153
	v_ashrrev_i32_e32 v131, 31, v130
	v_lshl_add_u64 v[132:133], v[130:131], 2, s[6:7]
	v_mov_b32_e32 v172, v242
	v_mov_b32_e32 v176, v243
	v_mov_b32_e32 v168, v244
	v_mov_b32_e32 v162, v245
	v_mov_b32_e32 v160, v246
	v_mov_b32_e32 v158, v247
	v_mov_b32_e32 v156, v248
	v_mov_b32_e32 v152, v249
	v_lshl_or_b32 v154, s29, 8, v159
	v_or_b32_e32 v174, 16, v130
	v_or_b32_e32 v170, 32, v130
	v_or_b32_e32 v164, 48, v130
	v_ashrrev_i32_e32 v155, 31, v154
	v_lshlrev_b64 v[130:131], 12, v[130:131]
	v_lshlrev_b64 v[166:167], 1, v[154:155]
	v_lshl_add_u64 v[130:131], s[16:17], 0, v[130:131]
	v_lshl_add_u64 v[154:155], v[130:131], 0, v[166:167]
	v_ashrrev_i32_e32 v175, 31, v174
	v_ashrrev_i32_e32 v171, 31, v170
	v_ashrrev_i32_e32 v165, 31, v164
	s_mov_b32 s21, 0x80000
	s_mov_b64 s[28:29], 0x80000
	s_waitcnt vmcnt(8)
	v_pk_mul_f32 v[104:105], v[104:105], v[176:177] op_sel_hi:[1,0]
	s_nop 0
	v_mul_f32_e32 v104, 0xbfb8aa3b, v104
	v_exp_f32_e32 v104, v104
	v_mul_f32_e32 v105, 0xbfb8aa3b, v105
	v_exp_f32_e32 v105, v105
	v_pk_mul_f32 v[126:127], v[126:127], v[172:173] op_sel_hi:[1,0]
	v_pk_mul_f32 v[124:125], v[124:125], v[172:173] op_sel_hi:[1,0]
	v_pk_mul_f32 v[122:123], v[122:123], v[172:173] op_sel_hi:[1,0]
	v_pk_mul_f32 v[120:121], v[120:121], v[172:173] op_sel_hi:[1,0]
	v_mul_f32_e32 v124, 0xbfb8aa3b, v124
	v_mul_f32_e32 v125, 0xbfb8aa3b, v125
	v_mul_f32_e32 v126, 0xbfb8aa3b, v126
	v_mul_f32_e32 v127, 0xbfb8aa3b, v127
	v_mul_f32_e32 v120, 0xbfb8aa3b, v120
	v_mul_f32_e32 v121, 0xbfb8aa3b, v121
	v_mul_f32_e32 v122, 0xbfb8aa3b, v122
	v_mul_f32_e32 v123, 0xbfb8aa3b, v123
	v_exp_f32_e32 v124, v124
	v_exp_f32_e32 v125, v125
	v_exp_f32_e32 v126, v126
	v_exp_f32_e32 v127, v127
	v_exp_f32_e32 v120, v120
	v_exp_f32_e32 v121, v121
	v_exp_f32_e32 v122, v122
	v_exp_f32_e32 v123, v123
	v_pk_mul_f32 v[114:115], v[114:115], v[172:173] op_sel_hi:[1,0]
	v_pk_mul_f32 v[112:113], v[112:113], v[172:173] op_sel_hi:[1,0]
	v_mul_f32_e32 v114, 0xbfb8aa3b, v114
	v_mul_f32_e32 v112, 0xbfb8aa3b, v112
	v_mul_f32_e32 v113, 0xbfb8aa3b, v113
	v_mul_f32_e32 v115, 0xbfb8aa3b, v115
	v_exp_f32_e32 v112, v112
	v_exp_f32_e32 v113, v113
	v_exp_f32_e32 v130, v114
	v_exp_f32_e32 v131, v115
	v_add_f32_e32 v114, 1.0, v124
	v_add_f32_e32 v115, 1.0, v125
	v_add_f32_e32 v124, 1.0, v126
	v_add_f32_e32 v125, 1.0, v127
	v_add_f32_e32 v120, 1.0, v120
	v_add_f32_e32 v121, 1.0, v121
	v_add_f32_e32 v122, 1.0, v122
	v_add_f32_e32 v123, 1.0, v123
	v_pk_mul_f32 v[118:119], v[118:119], v[172:173] op_sel_hi:[1,0]
	v_pk_mul_f32 v[116:117], v[116:117], v[172:173] op_sel_hi:[1,0]
	v_rcp_f32_e32 v114, v114
	v_rcp_f32_e32 v115, v115
	v_rcp_f32_e32 v124, v124
	v_rcp_f32_e32 v125, v125
	v_rcp_f32_e32 v120, v120
	v_rcp_f32_e32 v121, v121
	v_rcp_f32_e32 v122, v122
	v_rcp_f32_e32 v123, v123
	v_mul_f32_e32 v116, 0xbfb8aa3b, v116
	v_mul_f32_e32 v117, 0xbfb8aa3b, v117
	v_mul_f32_e32 v118, 0xbfb8aa3b, v118
	v_mul_f32_e32 v119, 0xbfb8aa3b, v119
	v_exp_f32_e32 v116, v116
	v_exp_f32_e32 v117, v117
	v_exp_f32_e32 v118, v118
	v_exp_f32_e32 v119, v119
	v_add_f32_e32 v112, 1.0, v112
	v_add_f32_e32 v113, 1.0, v113
	v_rcp_f32_e32 v126, v112
	v_rcp_f32_e32 v127, v113
	v_cvt_pk_bf16_f32 v112, v114, v115
	v_cvt_pk_bf16_f32 v113, v124, v125
	v_cvt_pk_bf16_f32 v114, v120, v121
	v_cvt_pk_bf16_f32 v115, v122, v123
	global_store_dwordx4 v[154:155], v[112:115], off
	v_add_f32_e32 v116, 1.0, v116
	v_add_f32_e32 v117, 1.0, v117
	v_add_f32_e32 v112, 1.0, v130
	v_add_f32_e32 v118, 1.0, v118
	v_add_f32_e32 v119, 1.0, v119
	v_rcp_f32_e32 v115, v112
	v_add_f32_e32 v112, 1.0, v131
	v_rcp_f32_e32 v116, v116
	v_rcp_f32_e32 v117, v117
	v_rcp_f32_e32 v118, v118
	v_rcp_f32_e32 v119, v119
	v_rcp_f32_e32 v120, v112
	v_cvt_pk_bf16_f32 v112, v116, v117
	v_cvt_pk_bf16_f32 v114, v126, v127
	v_cvt_pk_bf16_f32 v113, v118, v119
	v_cvt_pk_bf16_f32 v115, v115, v120
	v_pk_mul_f32 v[106:107], v[106:107], v[176:177] op_sel_hi:[1,0]
	v_add_f32_e32 v104, 1.0, v104
	global_store_dwordx4 v[154:155], v[112:115], off offset:256
	v_pk_mul_f32 v[110:111], v[110:111], v[176:177] op_sel_hi:[1,0]
	v_pk_mul_f32 v[108:109], v[108:109], v[176:177] op_sel_hi:[1,0]
	v_rcp_f32_e32 v114, v104
	v_add_f32_e32 v104, 1.0, v105
	v_mul_f32_e32 v105, 0xbfb8aa3b, v106
	v_mul_f32_e32 v108, 0xbfb8aa3b, v108
	v_mul_f32_e32 v109, 0xbfb8aa3b, v109
	v_mul_f32_e32 v110, 0xbfb8aa3b, v110
	v_mul_f32_e32 v111, 0xbfb8aa3b, v111
	v_exp_f32_e32 v105, v105
	v_mul_f32_e32 v106, 0xbfb8aa3b, v107
	v_exp_f32_e32 v108, v108
	v_exp_f32_e32 v109, v109
	v_exp_f32_e32 v110, v110
	v_exp_f32_e32 v111, v111
	v_exp_f32_e32 v106, v106
	v_rcp_f32_e32 v107, v104
	v_add_f32_e32 v104, 1.0, v105
	v_pk_mul_f32 v[96:97], v[96:97], v[176:177] op_sel_hi:[1,0]
	v_add_f32_e32 v108, 1.0, v108
	v_add_f32_e32 v109, 1.0, v109
	v_add_f32_e32 v110, 1.0, v110
	v_add_f32_e32 v111, 1.0, v111
	v_rcp_f32_e32 v115, v104
	v_add_f32_e32 v104, 1.0, v106
	v_mul_f32_e32 v96, 0xbfb8aa3b, v96
	v_rcp_f32_e32 v108, v108
	v_rcp_f32_e32 v109, v109
	v_rcp_f32_e32 v110, v110
	v_rcp_f32_e32 v111, v111
	v_rcp_f32_e32 v116, v104
	v_exp_f32_e32 v96, v96
	v_mul_f32_e32 v97, 0xbfb8aa3b, v97
	v_exp_f32_e32 v97, v97
	v_lshlrev_b64 v[112:113], 12, v[174:175]
	v_lshl_add_u64 v[112:113], s[16:17], 0, v[112:113]
	v_lshl_add_u64 v[112:113], v[112:113], 0, v[166:167]
	v_cvt_pk_bf16_f32 v104, v108, v109
	v_cvt_pk_bf16_f32 v105, v110, v111
	v_cvt_pk_bf16_f32 v106, v114, v107
	v_cvt_pk_bf16_f32 v107, v115, v116
	v_pk_mul_f32 v[98:99], v[98:99], v[176:177] op_sel_hi:[1,0]
	v_add_f32_e32 v96, 1.0, v96
	global_store_dwordx4 v[112:113], v[104:107], off
	v_pk_mul_f32 v[102:103], v[102:103], v[176:177] op_sel_hi:[1,0]
; __device__ __forceinline__ unsigned cvt_pk_bf16(float lo, float hi) { f32x2c_t v = {lo, hi}; bf16x2c_t b = __builtin_convertvector(v, bf16x2c_t); return __builtin_bit_cast(unsigned, b); }
;     static __device__ __forceinline__ float sg(float x) { return __builtin_amdgcn_rcpf(1.0f + __builtin_amdgcn_exp2f(-1.4426950408889634f * x)); }
;     __device__ __forceinline__ void operator()(const f32x4 (&acc)[2][2][4][2], const Unit& u, int wr, int wc, int fr, int fq) const {
;     ...
;             for (int m = 0; m < 4; ++m) { bf16_t* rowp = O + (size_t)(row0 + ai * HALF + m * 16) * ldc + col0;
;                 const float rs = rsv[ai][m];
; #pragma unroll
;                 for (int bj = 0; bj < 2; ++bj) { f32x4 v0 = acc[ai][bj][m][0], v1 = acc[ai][bj][m][1];
;                     if (RS) { v0 = v0 * rs; v1 = v1 * rs; }
;                     u32x4 w; w.x = cvt_pk_bf16(sg(v0[0]), sg(v0[1])); w.y = cvt_pk_bf16(sg(v0[2]), sg(v0[3])); w.z = cvt_pk_bf16(sg(v1[0]), sg(v1[1])); w.w = cvt_pk_bf16(sg(v1[2]), sg(v1[3]));
;                     *(u32x4*)(rowp + bj * HALF) = w; } }
	v_pk_mul_f32 v[100:101], v[100:101], v[176:177] op_sel_hi:[1,0]
	v_rcp_f32_e32 v104, v96
	v_add_f32_e32 v96, 1.0, v97
	v_mul_f32_e32 v97, 0xbfb8aa3b, v98
	v_mul_f32_e32 v100, 0xbfb8aa3b, v100
	v_mul_f32_e32 v101, 0xbfb8aa3b, v101
	v_mul_f32_e32 v102, 0xbfb8aa3b, v102
	v_mul_f32_e32 v103, 0xbfb8aa3b, v103
	v_exp_f32_e32 v97, v97
	v_mul_f32_e32 v98, 0xbfb8aa3b, v99
	v_exp_f32_e32 v100, v100
	v_exp_f32_e32 v101, v101
	v_exp_f32_e32 v102, v102
	v_exp_f32_e32 v103, v103
	v_exp_f32_e32 v98, v98
	v_rcp_f32_e32 v99, v96
	v_add_f32_e32 v96, 1.0, v97
	v_pk_mul_f32 v[88:89], v[88:89], v[168:169] op_sel_hi:[1,0]
	v_add_f32_e32 v100, 1.0, v100
	v_add_f32_e32 v101, 1.0, v101
	v_add_f32_e32 v102, 1.0, v102
	v_add_f32_e32 v103, 1.0, v103
	v_rcp_f32_e32 v105, v96
	v_add_f32_e32 v96, 1.0, v98
	v_mul_f32_e32 v88, 0xbfb8aa3b, v88
	v_rcp_f32_e32 v100, v100
	v_rcp_f32_e32 v101, v101
	v_rcp_f32_e32 v102, v102
	v_rcp_f32_e32 v103, v103
	v_rcp_f32_e32 v106, v96
	v_exp_f32_e32 v88, v88
	v_mul_f32_e32 v89, 0xbfb8aa3b, v89
	v_exp_f32_e32 v89, v89
	v_cvt_pk_bf16_f32 v96, v100, v101
	v_cvt_pk_bf16_f32 v97, v102, v103
	v_cvt_pk_bf16_f32 v98, v104, v99
	v_cvt_pk_bf16_f32 v99, v105, v106
	v_pk_mul_f32 v[90:91], v[90:91], v[168:169] op_sel_hi:[1,0]
	v_add_f32_e32 v88, 1.0, v88
	global_store_dwordx4 v[112:113], v[96:99], off offset:256
	v_pk_mul_f32 v[94:95], v[94:95], v[168:169] op_sel_hi:[1,0]
	v_pk_mul_f32 v[92:93], v[92:93], v[168:169] op_sel_hi:[1,0]
	v_rcp_f32_e32 v98, v88
	v_add_f32_e32 v88, 1.0, v89
	v_mul_f32_e32 v89, 0xbfb8aa3b, v90
	v_mul_f32_e32 v92, 0xbfb8aa3b, v92
	v_mul_f32_e32 v93, 0xbfb8aa3b, v93
	v_mul_f32_e32 v94, 0xbfb8aa3b, v94
	v_mul_f32_e32 v95, 0xbfb8aa3b, v95
	v_exp_f32_e32 v89, v89
	v_mul_f32_e32 v90, 0xbfb8aa3b, v91
	v_exp_f32_e32 v92, v92
	v_exp_f32_e32 v93, v93
	v_exp_f32_e32 v94, v94
	v_exp_f32_e32 v95, v95
	v_exp_f32_e32 v90, v90
	v_rcp_f32_e32 v91, v88
	v_add_f32_e32 v88, 1.0, v89
	v_pk_mul_f32 v[80:81], v[80:81], v[168:169] op_sel_hi:[1,0]
	v_add_f32_e32 v92, 1.0, v92
	v_add_f32_e32 v93, 1.0, v93
	v_add_f32_e32 v94, 1.0, v94
	v_add_f32_e32 v95, 1.0, v95
	v_rcp_f32_e32 v99, v88
	v_add_f32_e32 v88, 1.0, v90
	v_mul_f32_e32 v80, 0xbfb8aa3b, v80
	v_rcp_f32_e32 v92, v92
	v_rcp_f32_e32 v93, v93
	v_rcp_f32_e32 v94, v94
	v_rcp_f32_e32 v95, v95
	v_rcp_f32_e32 v100, v88
	v_exp_f32_e32 v80, v80
	v_mul_f32_e32 v81, 0xbfb8aa3b, v81
	v_exp_f32_e32 v81, v81
	v_lshlrev_b64 v[96:97], 12, v[170:171]
	v_lshl_add_u64 v[96:97], s[16:17], 0, v[96:97]
	v_lshl_add_u64 v[96:97], v[96:97], 0, v[166:167]
	v_cvt_pk_bf16_f32 v88, v92, v93
	v_cvt_pk_bf16_f32 v89, v94, v95
	v_cvt_pk_bf16_f32 v90, v98, v91
	v_cvt_pk_bf16_f32 v91, v99, v100
	v_pk_mul_f32 v[82:83], v[82:83], v[168:169] op_sel_hi:[1,0]
	v_add_f32_e32 v80, 1.0, v80
	global_store_dwordx4 v[96:97], v[88:91], off
	v_pk_mul_f32 v[86:87], v[86:87], v[168:169] op_sel_hi:[1,0]
	v_pk_mul_f32 v[84:85], v[84:85], v[168:169] op_sel_hi:[1,0]
	v_rcp_f32_e32 v88, v80
	v_add_f32_e32 v80, 1.0, v81
	v_mul_f32_e32 v81, 0xbfb8aa3b, v82
	v_mul_f32_e32 v84, 0xbfb8aa3b, v84
	v_mul_f32_e32 v85, 0xbfb8aa3b, v85
	v_mul_f32_e32 v86, 0xbfb8aa3b, v86
	v_mul_f32_e32 v87, 0xbfb8aa3b, v87
	v_exp_f32_e32 v81, v81
	v_mul_f32_e32 v82, 0xbfb8aa3b, v83
	v_exp_f32_e32 v84, v84
	v_exp_f32_e32 v85, v85
	v_exp_f32_e32 v86, v86
	v_exp_f32_e32 v87, v87
	v_exp_f32_e32 v82, v82
	v_rcp_f32_e32 v83, v80
	v_add_f32_e32 v80, 1.0, v81
	v_pk_mul_f32 v[72:73], v[72:73], v[162:163] op_sel_hi:[1,0]
	v_add_f32_e32 v84, 1.0, v84
	v_add_f32_e32 v85, 1.0, v85
	v_add_f32_e32 v86, 1.0, v86
	v_add_f32_e32 v87, 1.0, v87
	v_rcp_f32_e32 v89, v80
	v_add_f32_e32 v80, 1.0, v82
	v_mul_f32_e32 v72, 0xbfb8aa3b, v72
	v_rcp_f32_e32 v84, v84
	v_rcp_f32_e32 v85, v85
	v_rcp_f32_e32 v86, v86
	v_rcp_f32_e32 v87, v87
	v_rcp_f32_e32 v90, v80
	v_exp_f32_e32 v72, v72
	v_mul_f32_e32 v73, 0xbfb8aa3b, v73
	v_exp_f32_e32 v73, v73
	v_cvt_pk_bf16_f32 v80, v84, v85
	v_cvt_pk_bf16_f32 v81, v86, v87
	v_cvt_pk_bf16_f32 v82, v88, v83
	v_cvt_pk_bf16_f32 v83, v89, v90
	v_pk_mul_f32 v[74:75], v[74:75], v[162:163] op_sel_hi:[1,0]
	v_add_f32_e32 v72, 1.0, v72
	global_store_dwordx4 v[96:97], v[80:83], off offset:256
	v_pk_mul_f32 v[78:79], v[78:79], v[162:163] op_sel_hi:[1,0]
	v_pk_mul_f32 v[76:77], v[76:77], v[162:163] op_sel_hi:[1,0]
	v_rcp_f32_e32 v82, v72
	v_add_f32_e32 v72, 1.0, v73
	v_mul_f32_e32 v73, 0xbfb8aa3b, v74
	v_mul_f32_e32 v76, 0xbfb8aa3b, v76
	v_mul_f32_e32 v77, 0xbfb8aa3b, v77
	v_mul_f32_e32 v78, 0xbfb8aa3b, v78
	v_mul_f32_e32 v79, 0xbfb8aa3b, v79
	v_exp_f32_e32 v73, v73
	v_mul_f32_e32 v74, 0xbfb8aa3b, v75
	v_exp_f32_e32 v76, v76
	v_exp_f32_e32 v77, v77
	v_exp_f32_e32 v78, v78
	v_exp_f32_e32 v79, v79
	v_exp_f32_e32 v74, v74
	v_rcp_f32_e32 v75, v72
	v_add_f32_e32 v72, 1.0, v73
	v_pk_mul_f32 v[64:65], v[64:65], v[162:163] op_sel_hi:[1,0]
	v_add_f32_e32 v76, 1.0, v76
	v_add_f32_e32 v77, 1.0, v77
	v_add_f32_e32 v78, 1.0, v78
	v_add_f32_e32 v79, 1.0, v79
	v_rcp_f32_e32 v83, v72
	v_add_f32_e32 v72, 1.0, v74
	v_mul_f32_e32 v64, 0xbfb8aa3b, v64
	v_rcp_f32_e32 v76, v76
	v_rcp_f32_e32 v77, v77
	v_rcp_f32_e32 v78, v78
	v_rcp_f32_e32 v79, v79
	v_rcp_f32_e32 v84, v72
	v_exp_f32_e32 v64, v64
	v_mul_f32_e32 v65, 0xbfb8aa3b, v65
	v_exp_f32_e32 v65, v65
	v_lshlrev_b64 v[80:81], 12, v[164:165]
	v_lshl_add_u64 v[80:81], s[16:17], 0, v[80:81]
	v_lshl_add_u64 v[80:81], v[80:81], 0, v[166:167]
	v_cvt_pk_bf16_f32 v72, v76, v77
	v_cvt_pk_bf16_f32 v73, v78, v79
	v_cvt_pk_bf16_f32 v74, v82, v75
	v_cvt_pk_bf16_f32 v75, v83, v84
	v_pk_mul_f32 v[66:67], v[66:67], v[162:163] op_sel_hi:[1,0]
	v_add_f32_e32 v64, 1.0, v64
	global_store_dwordx4 v[80:81], v[72:75], off
	v_pk_mul_f32 v[70:71], v[70:71], v[162:163] op_sel_hi:[1,0]
; __device__ __forceinline__ unsigned cvt_pk_bf16(float lo, float hi) { f32x2c_t v = {lo, hi}; bf16x2c_t b = __builtin_convertvector(v, bf16x2c_t); return __builtin_bit_cast(unsigned, b); }
;     static __device__ __forceinline__ float sg(float x) { return __builtin_amdgcn_rcpf(1.0f + __builtin_amdgcn_exp2f(-1.4426950408889634f * x)); }
;     __device__ __forceinline__ void operator()(const f32x4 (&acc)[2][2][4][2], const Unit& u, int wr, int wc, int fr, int fq) const {
;     ...
;             for (int m = 0; m < 4; ++m) { bf16_t* rowp = O + (size_t)(row0 + ai * HALF + m * 16) * ldc + col0;
;                 const float rs = rsv[ai][m];
; #pragma unroll
;                 for (int bj = 0; bj < 2; ++bj) { f32x4 v0 = acc[ai][bj][m][0], v1 = acc[ai][bj][m][1];
;                     if (RS) { v0 = v0 * rs; v1 = v1 * rs; }
;                     u32x4 w; w.x = cvt_pk_bf16(sg(v0[0]), sg(v0[1])); w.y = cvt_pk_bf16(sg(v0[2]), sg(v0[3])); w.z = cvt_pk_bf16(sg(v1[0]), sg(v1[1])); w.w = cvt_pk_bf16(sg(v1[2]), sg(v1[3]));
;                     *(u32x4*)(rowp + bj * HALF) = w; } }
	v_pk_mul_f32 v[68:69], v[68:69], v[162:163] op_sel_hi:[1,0]
	v_rcp_f32_e32 v72, v64
	v_add_f32_e32 v64, 1.0, v65
	v_mul_f32_e32 v65, 0xbfb8aa3b, v66
	v_mul_f32_e32 v68, 0xbfb8aa3b, v68
	v_mul_f32_e32 v69, 0xbfb8aa3b, v69
	v_mul_f32_e32 v70, 0xbfb8aa3b, v70
	v_mul_f32_e32 v71, 0xbfb8aa3b, v71
	v_exp_f32_e32 v65, v65
	v_mul_f32_e32 v66, 0xbfb8aa3b, v67
	v_exp_f32_e32 v68, v68
	v_exp_f32_e32 v69, v69
	v_exp_f32_e32 v70, v70
	v_exp_f32_e32 v71, v71
	v_exp_f32_e32 v66, v66
	v_rcp_f32_e32 v67, v64
	v_add_f32_e32 v64, 1.0, v65
	v_pk_mul_f32 v[56:57], v[56:57], v[160:161] op_sel_hi:[1,0]
	v_add_f32_e32 v68, 1.0, v68
	v_add_f32_e32 v69, 1.0, v69
	v_add_f32_e32 v70, 1.0, v70
	v_add_f32_e32 v71, 1.0, v71
	v_rcp_f32_e32 v73, v64
	v_add_f32_e32 v64, 1.0, v66
	v_mul_f32_e32 v56, 0xbfb8aa3b, v56
	v_rcp_f32_e32 v68, v68
	v_rcp_f32_e32 v69, v69
	v_rcp_f32_e32 v70, v70
	v_rcp_f32_e32 v71, v71
	v_rcp_f32_e32 v74, v64
	v_exp_f32_e32 v56, v56
	v_mul_f32_e32 v57, 0xbfb8aa3b, v57
	v_exp_f32_e32 v57, v57
	v_cvt_pk_bf16_f32 v64, v68, v69
	v_cvt_pk_bf16_f32 v65, v70, v71
	v_cvt_pk_bf16_f32 v66, v72, v67
	v_cvt_pk_bf16_f32 v67, v73, v74
	v_pk_mul_f32 v[60:61], v[60:61], v[160:161] op_sel_hi:[1,0]
	v_pk_mul_f32 v[58:59], v[58:59], v[160:161] op_sel_hi:[1,0]
	v_add_f32_e32 v56, 1.0, v56
	global_store_dwordx4 v[80:81], v[64:67], off offset:256
	v_pk_mul_f32 v[62:63], v[62:63], v[160:161] op_sel_hi:[1,0]
	v_mul_f32_e32 v60, 0xbfb8aa3b, v60
	v_mul_f32_e32 v61, 0xbfb8aa3b, v61
	v_rcp_f32_e32 v66, v56
	v_add_f32_e32 v56, 1.0, v57
	v_mul_f32_e32 v57, 0xbfb8aa3b, v58
	v_exp_f32_e32 v60, v60
	v_exp_f32_e32 v61, v61
	v_mul_f32_e32 v62, 0xbfb8aa3b, v62
	v_mul_f32_e32 v63, 0xbfb8aa3b, v63
	v_exp_f32_e32 v57, v57
	v_mul_f32_e32 v58, 0xbfb8aa3b, v59
	v_exp_f32_e32 v62, v62
	v_exp_f32_e32 v63, v63
	v_exp_f32_e32 v58, v58
	v_add_f32_e32 v60, 1.0, v60
	v_add_f32_e32 v61, 1.0, v61
	v_rcp_f32_e32 v59, v56
	v_add_f32_e32 v56, 1.0, v57
	v_pk_mul_f32 v[48:49], v[48:49], v[160:161] op_sel_hi:[1,0]
	v_rcp_f32_e32 v60, v60
	v_rcp_f32_e32 v61, v61
	v_add_f32_e32 v62, 1.0, v62
	v_add_f32_e32 v63, 1.0, v63
	v_rcp_f32_e32 v67, v56
	v_add_f32_e32 v56, 1.0, v58
	v_mul_f32_e32 v48, 0xbfb8aa3b, v48
	v_rcp_f32_e32 v62, v62
	v_rcp_f32_e32 v63, v63
	v_rcp_f32_e32 v68, v56
	v_exp_f32_e32 v48, v48
	v_mul_f32_e32 v49, 0xbfb8aa3b, v49
	v_exp_f32_e32 v49, v49
	v_cvt_pk_bf16_f32 v56, v60, v61
	v_add_co_u32_e32 v60, vcc, s21, v154
	v_cvt_pk_bf16_f32 v57, v62, v63
	v_cvt_pk_bf16_f32 v58, v66, v59
	v_cvt_pk_bf16_f32 v59, v67, v68
	v_addc_co_u32_e32 v61, vcc, 0, v155, vcc
	v_pk_mul_f32 v[50:51], v[50:51], v[160:161] op_sel_hi:[1,0]
	v_add_f32_e32 v48, 1.0, v48
	global_store_dwordx4 v[60:61], v[56:59], off
	v_pk_mul_f32 v[54:55], v[54:55], v[160:161] op_sel_hi:[1,0]
	v_pk_mul_f32 v[52:53], v[52:53], v[160:161] op_sel_hi:[1,0]
	v_rcp_f32_e32 v56, v48
	v_add_f32_e32 v48, 1.0, v49
	v_mul_f32_e32 v49, 0xbfb8aa3b, v50
	v_mul_f32_e32 v52, 0xbfb8aa3b, v52
	v_mul_f32_e32 v53, 0xbfb8aa3b, v53
	v_mul_f32_e32 v54, 0xbfb8aa3b, v54
	v_mul_f32_e32 v55, 0xbfb8aa3b, v55
	v_exp_f32_e32 v49, v49
	v_mul_f32_e32 v50, 0xbfb8aa3b, v51
	v_exp_f32_e32 v52, v52
	v_exp_f32_e32 v53, v53
	v_exp_f32_e32 v54, v54
	v_exp_f32_e32 v55, v55
	v_exp_f32_e32 v50, v50
	v_rcp_f32_e32 v51, v48
	v_add_f32_e32 v48, 1.0, v49
	v_pk_mul_f32 v[40:41], v[40:41], v[158:159] op_sel_hi:[1,0]
	v_add_f32_e32 v52, 1.0, v52
	v_add_f32_e32 v53, 1.0, v53
	v_add_f32_e32 v54, 1.0, v54
	v_add_f32_e32 v55, 1.0, v55
	v_rcp_f32_e32 v57, v48
	v_add_f32_e32 v48, 1.0, v50
	v_mul_f32_e32 v40, 0xbfb8aa3b, v40
	v_rcp_f32_e32 v52, v52
	v_rcp_f32_e32 v53, v53
	v_rcp_f32_e32 v54, v54
	v_rcp_f32_e32 v55, v55
	v_rcp_f32_e32 v58, v48
	v_exp_f32_e32 v40, v40
	v_mul_f32_e32 v41, 0xbfb8aa3b, v41
	v_exp_f32_e32 v41, v41
	v_lshl_add_u64 v[64:65], v[154:155], 0, s[28:29]
	v_cvt_pk_bf16_f32 v48, v52, v53
	v_cvt_pk_bf16_f32 v49, v54, v55
	v_cvt_pk_bf16_f32 v50, v56, v51
	v_cvt_pk_bf16_f32 v51, v57, v58
	v_pk_mul_f32 v[44:45], v[44:45], v[158:159] op_sel_hi:[1,0]
	v_pk_mul_f32 v[42:43], v[42:43], v[158:159] op_sel_hi:[1,0]
	v_add_f32_e32 v40, 1.0, v40
	global_store_dwordx4 v[64:65], v[48:51], off offset:256
	v_pk_mul_f32 v[46:47], v[46:47], v[158:159] op_sel_hi:[1,0]
	v_mul_f32_e32 v44, 0xbfb8aa3b, v44
	v_mul_f32_e32 v45, 0xbfb8aa3b, v45
	v_rcp_f32_e32 v50, v40
	v_add_f32_e32 v40, 1.0, v41
	v_mul_f32_e32 v41, 0xbfb8aa3b, v42
	v_exp_f32_e32 v44, v44
	v_exp_f32_e32 v45, v45
	v_mul_f32_e32 v46, 0xbfb8aa3b, v46
	v_mul_f32_e32 v47, 0xbfb8aa3b, v47
	v_exp_f32_e32 v41, v41
	v_mul_f32_e32 v42, 0xbfb8aa3b, v43
	v_exp_f32_e32 v46, v46
	v_exp_f32_e32 v47, v47
	v_exp_f32_e32 v42, v42
	v_add_f32_e32 v44, 1.0, v44
	v_add_f32_e32 v45, 1.0, v45
	v_rcp_f32_e32 v43, v40
	v_add_f32_e32 v40, 1.0, v41
	v_pk_mul_f32 v[32:33], v[32:33], v[158:159] op_sel_hi:[1,0]
	v_rcp_f32_e32 v44, v44
	v_rcp_f32_e32 v45, v45
	v_add_f32_e32 v46, 1.0, v46
	v_add_f32_e32 v47, 1.0, v47
	v_rcp_f32_e32 v51, v40
	v_add_f32_e32 v40, 1.0, v42
	v_mul_f32_e32 v32, 0xbfb8aa3b, v32
	v_rcp_f32_e32 v46, v46
	v_rcp_f32_e32 v47, v47
	v_rcp_f32_e32 v52, v40
	v_exp_f32_e32 v32, v32
	v_mul_f32_e32 v33, 0xbfb8aa3b, v33
	v_exp_f32_e32 v33, v33
	s_mov_b32 s21, 0x90000
	v_cvt_pk_bf16_f32 v40, v44, v45
	v_add_co_u32_e32 v44, vcc, s21, v154
	v_cvt_pk_bf16_f32 v41, v46, v47
	v_cvt_pk_bf16_f32 v42, v50, v43
	v_cvt_pk_bf16_f32 v43, v51, v52
	v_addc_co_u32_e32 v45, vcc, 0, v155, vcc
	v_pk_mul_f32 v[34:35], v[34:35], v[158:159] op_sel_hi:[1,0]
	v_add_f32_e32 v32, 1.0, v32
	global_store_dwordx4 v[44:45], v[40:43], off
	v_pk_mul_f32 v[38:39], v[38:39], v[158:159] op_sel_hi:[1,0]
	v_pk_mul_f32 v[36:37], v[36:37], v[158:159] op_sel_hi:[1,0]
	v_rcp_f32_e32 v40, v32
; __device__ __forceinline__ unsigned cvt_pk_bf16(float lo, float hi) { f32x2c_t v = {lo, hi}; bf16x2c_t b = __builtin_convertvector(v, bf16x2c_t); return __builtin_bit_cast(unsigned, b); }
;     static __device__ __forceinline__ float sg(float x) { return __builtin_amdgcn_rcpf(1.0f + __builtin_amdgcn_exp2f(-1.4426950408889634f * x)); }
; #define PG8_BAR __builtin_amdgcn_s_barrier()
;     __device__ __forceinline__ void operator()(const f32x4 (&acc)[2][2][4][2], const Unit& u, int wr, int wc, int fr, int fq) const {
;     ...
;             for (int m = 0; m < 4; ++m) { bf16_t* rowp = O + (size_t)(row0 + ai * HALF + m * 16) * ldc + col0;
;                 const float rs = rsv[ai][m];
; #pragma unroll
;                 for (int bj = 0; bj < 2; ++bj) { f32x4 v0 = acc[ai][bj][m][0], v1 = acc[ai][bj][m][1];
;                     if (RS) { v0 = v0 * rs; v1 = v1 * rs; }
;                     u32x4 w; w.x = cvt_pk_bf16(sg(v0[0]), sg(v0[1])); w.y = cvt_pk_bf16(sg(v0[2]), sg(v0[3])); w.z = cvt_pk_bf16(sg(v1[0]), sg(v1[1])); w.w = cvt_pk_bf16(sg(v1[2]), sg(v1[3]));
;                     *(u32x4*)(rowp + bj * HALF) = w; } }
; template <class Epi, class Sched, bool ALIGN_EPI = false, bool SP2 = false>
; __device__ __forceinline__ void gemm_phase(PG8_LAS unsigned char* lds, const Gemm g, const Sched& S, const Epi& E) {
;     ...
;         if constexpr (ALIGN_EPI) { if (wr == 0) PG8_BAR; }
;         if constexpr (!Epi::AFTER_DRAIN) { E(acc, cur, wr, wc, fr, fq); S.done(cur); }
;         if (!has_next) break;
; #pragma unroll
;         for (int a = 0; a < 2; ++a)
; #pragma unroll
;             for (int b = 0; b < 2; ++b)
; #pragma unroll
;                 for (int m = 0; m < 4; ++m)
; #pragma unroll
;                     for (int n = 0; n < 2; ++n) acc[a][b][m][n] = (f32x4){0.f, 0.f, 0.f, 0.f};
;         cur = nxt; cA = nA; cB = nB; ++ui;
;         if constexpr (ALIGN_EPI) { if (wr == 1) PG8_BAR; }
	v_add_f32_e32 v32, 1.0, v33
	v_mul_f32_e32 v33, 0xbfb8aa3b, v34
	v_mul_f32_e32 v36, 0xbfb8aa3b, v36
	v_mul_f32_e32 v37, 0xbfb8aa3b, v37
	v_mul_f32_e32 v38, 0xbfb8aa3b, v38
	v_mul_f32_e32 v39, 0xbfb8aa3b, v39
	v_exp_f32_e32 v33, v33
	v_mul_f32_e32 v34, 0xbfb8aa3b, v35
	v_exp_f32_e32 v36, v36
	v_exp_f32_e32 v37, v37
	v_exp_f32_e32 v38, v38
	v_exp_f32_e32 v39, v39
	v_exp_f32_e32 v34, v34
	v_rcp_f32_e32 v35, v32
	v_add_f32_e32 v32, 1.0, v33
	v_pk_mul_f32 v[24:25], v[24:25], v[156:157] op_sel_hi:[1,0]
	v_add_f32_e32 v36, 1.0, v36
	v_add_f32_e32 v37, 1.0, v37
	v_add_f32_e32 v38, 1.0, v38
	v_add_f32_e32 v39, 1.0, v39
	v_rcp_f32_e32 v41, v32
	v_add_f32_e32 v32, 1.0, v34
	v_mul_f32_e32 v24, 0xbfb8aa3b, v24
	v_rcp_f32_e32 v36, v36
	v_rcp_f32_e32 v37, v37
	v_rcp_f32_e32 v38, v38
	v_rcp_f32_e32 v39, v39
	v_rcp_f32_e32 v42, v32
	v_exp_f32_e32 v24, v24
	v_mul_f32_e32 v25, 0xbfb8aa3b, v25
	v_exp_f32_e32 v25, v25
	v_lshl_add_u64 v[48:49], v[154:155], 0, s[84:85]
	v_cvt_pk_bf16_f32 v32, v36, v37
	v_cvt_pk_bf16_f32 v33, v38, v39
	v_cvt_pk_bf16_f32 v34, v40, v35
	v_cvt_pk_bf16_f32 v35, v41, v42
	v_pk_mul_f32 v[28:29], v[28:29], v[156:157] op_sel_hi:[1,0]
	v_pk_mul_f32 v[26:27], v[26:27], v[156:157] op_sel_hi:[1,0]
	v_add_f32_e32 v24, 1.0, v24
	global_store_dwordx4 v[48:49], v[32:35], off offset:256
	v_pk_mul_f32 v[30:31], v[30:31], v[156:157] op_sel_hi:[1,0]
	v_mul_f32_e32 v28, 0xbfb8aa3b, v28
	v_mul_f32_e32 v29, 0xbfb8aa3b, v29
	v_rcp_f32_e32 v34, v24
	v_add_f32_e32 v24, 1.0, v25
	v_mul_f32_e32 v25, 0xbfb8aa3b, v26
	v_exp_f32_e32 v28, v28
	v_exp_f32_e32 v29, v29
	v_mul_f32_e32 v30, 0xbfb8aa3b, v30
	v_mul_f32_e32 v31, 0xbfb8aa3b, v31
	v_exp_f32_e32 v25, v25
	v_mul_f32_e32 v26, 0xbfb8aa3b, v27
	v_exp_f32_e32 v30, v30
	v_exp_f32_e32 v31, v31
	v_exp_f32_e32 v26, v26
	v_add_f32_e32 v28, 1.0, v28
	v_add_f32_e32 v29, 1.0, v29
	v_rcp_f32_e32 v27, v24
	v_add_f32_e32 v24, 1.0, v25
	v_pk_mul_f32 v[16:17], v[16:17], v[156:157] op_sel_hi:[1,0]
	v_rcp_f32_e32 v28, v28
	v_rcp_f32_e32 v29, v29
	v_add_f32_e32 v30, 1.0, v30
	v_add_f32_e32 v31, 1.0, v31
	v_rcp_f32_e32 v35, v24
	v_add_f32_e32 v24, 1.0, v26
	v_mul_f32_e32 v16, 0xbfb8aa3b, v16
	v_rcp_f32_e32 v30, v30
	v_rcp_f32_e32 v31, v31
	v_rcp_f32_e32 v36, v24
	v_exp_f32_e32 v16, v16
	v_mul_f32_e32 v17, 0xbfb8aa3b, v17
	v_exp_f32_e32 v17, v17
	s_mov_b32 s21, 0xa0000
	v_cvt_pk_bf16_f32 v24, v28, v29
	v_add_co_u32_e32 v28, vcc, s21, v154
	v_cvt_pk_bf16_f32 v25, v30, v31
	v_cvt_pk_bf16_f32 v26, v34, v27
	v_cvt_pk_bf16_f32 v27, v35, v36
	v_addc_co_u32_e32 v29, vcc, 0, v155, vcc
	v_pk_mul_f32 v[18:19], v[18:19], v[156:157] op_sel_hi:[1,0]
	v_add_f32_e32 v16, 1.0, v16
	global_store_dwordx4 v[28:29], v[24:27], off
	v_pk_mul_f32 v[22:23], v[22:23], v[156:157] op_sel_hi:[1,0]
	v_pk_mul_f32 v[20:21], v[20:21], v[156:157] op_sel_hi:[1,0]
	v_rcp_f32_e32 v24, v16
	v_add_f32_e32 v16, 1.0, v17
	v_mul_f32_e32 v17, 0xbfb8aa3b, v18
	v_mul_f32_e32 v20, 0xbfb8aa3b, v20
	v_mul_f32_e32 v21, 0xbfb8aa3b, v21
	v_mul_f32_e32 v22, 0xbfb8aa3b, v22
	v_mul_f32_e32 v23, 0xbfb8aa3b, v23
	v_exp_f32_e32 v17, v17
	v_mul_f32_e32 v18, 0xbfb8aa3b, v19
	v_exp_f32_e32 v20, v20
	v_exp_f32_e32 v21, v21
	v_exp_f32_e32 v22, v22
	v_exp_f32_e32 v23, v23
	v_exp_f32_e32 v18, v18
	v_rcp_f32_e32 v19, v16
	v_add_f32_e32 v16, 1.0, v17
	v_pk_mul_f32 v[8:9], v[8:9], v[152:153] op_sel_hi:[1,0]
	v_add_f32_e32 v20, 1.0, v20
	v_add_f32_e32 v21, 1.0, v21
	v_add_f32_e32 v22, 1.0, v22
	v_add_f32_e32 v23, 1.0, v23
	v_rcp_f32_e32 v25, v16
	v_add_f32_e32 v16, 1.0, v18
	v_mul_f32_e32 v8, 0xbfb8aa3b, v8
	v_rcp_f32_e32 v20, v20
	v_rcp_f32_e32 v21, v21
	v_rcp_f32_e32 v22, v22
	v_rcp_f32_e32 v23, v23
	v_rcp_f32_e32 v26, v16
	v_exp_f32_e32 v8, v8
	v_mul_f32_e32 v9, 0xbfb8aa3b, v9
	v_exp_f32_e32 v9, v9
	v_lshl_add_u64 v[32:33], v[154:155], 0, s[86:87]
	v_cvt_pk_bf16_f32 v16, v20, v21
	v_cvt_pk_bf16_f32 v17, v22, v23
	v_cvt_pk_bf16_f32 v18, v24, v19
	v_cvt_pk_bf16_f32 v19, v25, v26
	v_pk_mul_f32 v[12:13], v[12:13], v[152:153] op_sel_hi:[1,0]
	v_pk_mul_f32 v[10:11], v[10:11], v[152:153] op_sel_hi:[1,0]
	v_add_f32_e32 v8, 1.0, v8
	global_store_dwordx4 v[32:33], v[16:19], off offset:256
	v_pk_mul_f32 v[14:15], v[14:15], v[152:153] op_sel_hi:[1,0]
	v_mul_f32_e32 v12, 0xbfb8aa3b, v12
	v_mul_f32_e32 v13, 0xbfb8aa3b, v13
	v_rcp_f32_e32 v18, v8
	v_add_f32_e32 v8, 1.0, v9
	v_mul_f32_e32 v9, 0xbfb8aa3b, v10
	v_exp_f32_e32 v12, v12
	v_exp_f32_e32 v13, v13
	v_mul_f32_e32 v14, 0xbfb8aa3b, v14
	v_mul_f32_e32 v15, 0xbfb8aa3b, v15
	v_exp_f32_e32 v9, v9
	v_mul_f32_e32 v10, 0xbfb8aa3b, v11
	v_exp_f32_e32 v14, v14
	v_exp_f32_e32 v15, v15
	v_exp_f32_e32 v10, v10
	v_add_f32_e32 v12, 1.0, v12
	v_add_f32_e32 v13, 1.0, v13
	v_rcp_f32_e32 v11, v8
	v_add_f32_e32 v8, 1.0, v9
	v_pk_mul_f32 v[0:1], v[0:1], v[152:153] op_sel_hi:[1,0]
	v_rcp_f32_e32 v12, v12
	v_rcp_f32_e32 v13, v13
	v_add_f32_e32 v14, 1.0, v14
	v_add_f32_e32 v15, 1.0, v15
	v_rcp_f32_e32 v19, v8
	v_add_f32_e32 v8, 1.0, v10
	v_mul_f32_e32 v0, 0xbfb8aa3b, v0
	v_rcp_f32_e32 v14, v14
	v_rcp_f32_e32 v15, v15
	v_rcp_f32_e32 v20, v8
	v_exp_f32_e32 v0, v0
	v_mul_f32_e32 v1, 0xbfb8aa3b, v1
	v_exp_f32_e32 v1, v1
	s_mov_b32 s21, 0xb0000
	v_cvt_pk_bf16_f32 v8, v12, v13
	v_add_co_u32_e32 v12, vcc, s21, v154
	v_cvt_pk_bf16_f32 v9, v14, v15
	v_cvt_pk_bf16_f32 v10, v18, v11
	v_cvt_pk_bf16_f32 v11, v19, v20
	v_addc_co_u32_e32 v13, vcc, 0, v155, vcc
	v_pk_mul_f32 v[2:3], v[2:3], v[152:153] op_sel_hi:[1,0]
	v_add_f32_e32 v0, 1.0, v0
	global_store_dwordx4 v[12:13], v[8:11], off
	v_pk_mul_f32 v[6:7], v[6:7], v[152:153] op_sel_hi:[1,0]
	v_pk_mul_f32 v[4:5], v[4:5], v[152:153] op_sel_hi:[1,0]
	v_rcp_f32_e32 v8, v0
	v_add_f32_e32 v0, 1.0, v1
	v_mul_f32_e32 v1, 0xbfb8aa3b, v2
	v_mul_f32_e32 v4, 0xbfb8aa3b, v4
	v_mul_f32_e32 v5, 0xbfb8aa3b, v5
	v_mul_f32_e32 v6, 0xbfb8aa3b, v6
	v_mul_f32_e32 v7, 0xbfb8aa3b, v7
	v_exp_f32_e32 v1, v1
	v_mul_f32_e32 v2, 0xbfb8aa3b, v3
	v_exp_f32_e32 v4, v4
	v_exp_f32_e32 v5, v5
	v_exp_f32_e32 v6, v6
	v_exp_f32_e32 v7, v7
	v_exp_f32_e32 v2, v2
	v_rcp_f32_e32 v3, v0
	v_add_f32_e32 v0, 1.0, v1
	v_add_f32_e32 v4, 1.0, v4
	v_add_f32_e32 v5, 1.0, v5
	v_add_f32_e32 v6, 1.0, v6
	v_add_f32_e32 v7, 1.0, v7
	v_rcp_f32_e32 v9, v0
	v_add_f32_e32 v0, 1.0, v2
	v_rcp_f32_e32 v4, v4
	v_rcp_f32_e32 v5, v5
	v_rcp_f32_e32 v6, v6
	v_rcp_f32_e32 v7, v7
	v_rcp_f32_e32 v10, v0
	v_lshl_add_u64 v[16:17], v[154:155], 0, s[88:89]
	v_cvt_pk_bf16_f32 v0, v4, v5
	v_cvt_pk_bf16_f32 v1, v6, v7
	v_cvt_pk_bf16_f32 v2, v8, v3
	v_cvt_pk_bf16_f32 v3, v9, v10
	s_andn2_b64 vcc, exec, s[40:41]
	s_mov_b64 s[28:29], -1
	global_store_dwordx4 v[16:17], v[0:3], off offset:256
	s_cbranch_vccnz .LBB0_1118
	s_andn2_b64 vcc, exec, s[14:15]
	s_cbranch_vccnz .LBB0_1117
	s_barrier
	s_branch .LBB0_1117
